# Epilogue row-statistic butterflies (lane^16 / lane^32): LDS ds_bpermute round trips replaced by v_permlane16/32_swap at 55 sites (EpiSwiglu, EpiWin rstd)
# baseline (speedup 1.0000x reference)
.LBB0_169:
	v_mov_b32_e32 v142, v149
	v_mov_b32_e32 v180, v147
	s_add_i32 s22, 0, 0x21000
	v_add_u32_e32 v181, s88, v142
	v_lshlrev_b32_e32 v142, 4, v180
	v_lshlrev_b32_e32 v143, 6, v181
	s_waitcnt vmcnt(16)
	s_barrier
	v_add3_u32 v146, s22, v142, v143
	ds_read_b128 v[142:145], v146
	ds_read_b128 v[154:157], v146 offset:1024
	ds_read_b128 v[158:161], v146 offset:2048
	ds_read_b128 v[162:165], v146 offset:3072
	v_and_b32_e32 v150, 64, v225
	v_xor_b32_e32 v148, 16, v225
	v_add_u32_e32 v150, 64, v150
	v_cmp_lt_i32_e32 vcc, v148, v150
	s_waitcnt lgkmcnt(0)
	v_mov_b32_e32 v166, v143
	v_mov_b32_e32 v167, v144
	v_mov_b32_e32 v143, v145
	v_cndmask_b32_e32 v148, v225, v148, vcc
	v_pk_add_f32 v[142:143], v[166:167], v[142:143]
	v_lshlrev_b32_e32 v182, 2, v148
	v_add_f32_e32 v142, v142, v143
	v_mov_b32_e32 v143, v142
	s_nop 1
	v_permlane16_swap_b32_e32 v143, v142
	v_xor_b32_e32 v144, 32, v225
	v_cmp_lt_i32_e32 vcc, v144, v150
	v_mov_b32_e32 v178, v155
	v_mov_b32_e32 v179, v156
	v_cndmask_b32_e32 v144, v225, v144, vcc
	v_lshlrev_b32_e32 v183, 2, v144
	s_waitcnt lgkmcnt(0)
	v_add_f32_e32 v148, v142, v143
	v_mov_b32_e32 v150, v148
	s_nop 1
	v_permlane32_swap_b32_e32 v150, v148
	v_mov_b32_e32 v155, v157
	v_pk_add_f32 v[154:155], v[178:179], v[154:155]
	ds_read_b128 v[142:145], v146 offset:8192
	ds_read_b128 v[166:169], v146 offset:9216
	ds_read_b128 v[170:173], v146 offset:10240
	ds_read_b128 v[174:177], v146 offset:11264
	s_and_b64 vcc, exec, s[6:7]
	s_waitcnt lgkmcnt(0)
	v_add_f32_e32 v146, v148, v150
	v_add_f32_e32 v148, v154, v155
	v_mov_b32_e32 v154, v159
	v_mov_b32_e32 v155, v160
	v_mov_b32_e32 v159, v161
	v_pk_add_f32 v[154:155], v[154:155], v[158:159]
	v_mov_b32_e32 v150, v148
	s_nop 1
	v_permlane16_swap_b32_e32 v150, v148
	v_add_f32_e32 v152, v154, v155
	v_mov_b32_e32 v154, v152
	s_nop 1
	v_permlane16_swap_b32_e32 v154, v152
	v_fmamk_f32 v146, v146, 0x3a800000, v226
	v_rsq_f32_e32 v156, v146
	s_waitcnt lgkmcnt(0)
	v_add_f32_e32 v146, v148, v150
	v_mov_b32_e32 v155, v164
	v_add_f32_e32 v150, v152, v154
	v_mov_b32_e32 v154, v163
	v_mov_b32_e32 v163, v165
	v_pk_add_f32 v[154:155], v[154:155], v[162:163]
	v_mov_b32_e32 v148, v146
	s_nop 1
	v_permlane32_swap_b32_e32 v148, v146
	v_add_f32_e32 v155, v154, v155
	v_mov_b32_e32 v158, v143
	v_mov_b32_e32 v159, v144
	v_mov_b32_e32 v143, v145
	v_mov_b32_e32 v157, v155
	s_nop 1
	v_permlane16_swap_b32_e32 v157, v155
	v_pk_add_f32 v[142:143], v[158:159], v[142:143]
	v_mov_b32_e32 v152, v150
	s_nop 1
	v_permlane32_swap_b32_e32 v152, v150
	v_add_f32_e32 v142, v142, v143
	v_mov_b32_e32 v143, v142
	s_nop 1
	v_permlane16_swap_b32_e32 v143, v142
	s_waitcnt lgkmcnt(0)
	v_add_f32_e32 v146, v146, v148
	v_fmamk_f32 v146, v146, 0x3a800000, v226
	v_add_f32_e32 v148, v155, v157
	v_rsq_f32_e32 v154, v146
	v_add_f32_e32 v146, v150, v152
	v_mov_b32_e32 v150, v148
	s_nop 1
	v_permlane32_swap_b32_e32 v150, v148
	v_add_f32_e32 v145, v142, v143
	v_mov_b32_e32 v142, v167
	v_mov_b32_e32 v143, v168
	v_mov_b32_e32 v167, v169
	v_fmamk_f32 v144, v146, 0x3a800000, v226
	v_mov_b32_e32 v146, v145
	s_nop 1
	v_permlane32_swap_b32_e32 v146, v145
	v_pk_add_f32 v[142:143], v[142:143], v[166:167]
	v_rsq_f32_e32 v152, v144
	v_add_f32_e32 v142, v142, v143
	v_mov_b32_e32 v143, v142
	s_nop 1
	v_permlane16_swap_b32_e32 v143, v142
	s_waitcnt lgkmcnt(0)
	v_add_f32_e32 v144, v148, v150
	v_fmamk_f32 v144, v144, 0x3a800000, v226
	v_rsq_f32_e32 v150, v144
	v_add_f32_e32 v144, v145, v146
	v_fmamk_f32 v144, v144, 0x3a800000, v226
	v_rsq_f32_e32 v148, v144
	v_add_f32_e32 v144, v142, v143
	v_mov_b32_e32 v142, v171
	v_mov_b32_e32 v143, v172
	v_mov_b32_e32 v171, v173
	v_pk_add_f32 v[142:143], v[142:143], v[170:171]
	v_pk_mul_f32 v[158:159], v[126:127], v[156:157] op_sel_hi:[1,0]
	v_add_f32_e32 v146, v142, v143
	v_mov_b32_e32 v142, v175
	v_mov_b32_e32 v143, v176
	v_mov_b32_e32 v175, v177
	v_pk_add_f32 v[142:143], v[142:143], v[174:175]
	v_mul_f32_e32 v126, 0xbfb8aa3b, v158
	v_add_f32_e32 v142, v142, v143
	v_mov_b32_e32 v143, v142
	s_nop 1
	v_permlane16_swap_b32_e32 v143, v142
	v_exp_f32_e32 v127, v126
	v_pk_mul_f32 v[128:129], v[128:129], v[156:157] op_sel_hi:[1,0]
	v_pk_mul_f32 v[122:123], v[122:123], v[156:157] op_sel_hi:[1,0]
	v_pk_mul_f32 v[118:119], v[118:119], v[156:157] op_sel_hi:[1,0]
	s_waitcnt lgkmcnt(0)
	v_add_f32_e32 v142, v142, v143
	v_mov_b32_e32 v143, v142
	s_nop 1
	v_permlane32_swap_b32_e32 v143, v142
	v_add_f32_e32 v127, 1.0, v127
	v_rcp_f32_e32 v162, v127
	v_pk_mul_f32 v[122:123], v[158:159], v[122:123]
	v_pk_mul_f32 v[124:125], v[124:125], v[156:157] op_sel_hi:[1,0]
	s_waitcnt lgkmcnt(0)
	v_add_f32_e32 v142, v142, v143
	v_mul_f32_e32 v143, 0xbfb8aa3b, v159
	v_exp_f32_e32 v143, v143
	v_pk_mul_f32 v[114:115], v[114:115], v[156:157] op_sel_hi:[1,0]
	v_pk_mul_f32 v[124:125], v[128:129], v[124:125]
	v_pk_mul_f32 v[114:115], v[118:119], v[114:115]
	v_add_f32_e32 v127, 1.0, v143
	v_rcp_f32_e32 v163, v127
	v_mul_f32_e32 v127, 0xbfb8aa3b, v128
	v_exp_f32_e32 v127, v127
	v_mul_f32_e32 v143, 0xbfb8aa3b, v129
	v_exp_f32_e32 v143, v143
	v_mul_f32_e32 v128, 0xbfb8aa3b, v119
	v_add_f32_e32 v127, 1.0, v127
	v_rcp_f32_e32 v158, v127
	v_add_f32_e32 v127, 1.0, v143
	v_rcp_f32_e32 v159, v127
	v_mul_f32_e32 v127, 0xbfb8aa3b, v118
	v_exp_f32_e32 v127, v127
	v_pk_mul_f32 v[118:119], v[120:121], v[156:157] op_sel_hi:[1,0]
	v_exp_f32_e32 v129, v128
	v_mul_f32_e32 v120, 0xbfb8aa3b, v118
	v_mul_f32_e32 v121, 0xbfb8aa3b, v119
	v_exp_f32_e32 v120, v120
	v_exp_f32_e32 v121, v121
	v_mov_b32_e32 v145, v144
	s_nop 1
	v_permlane32_swap_b32_e32 v145, v144
	v_mov_b32_e32 v155, v146
	s_nop 1
	v_permlane16_swap_b32_e32 v155, v146
	v_add_f32_e32 v127, 1.0, v127
	v_rcp_f32_e32 v128, v127
	v_add_f32_e32 v127, 1.0, v129
	v_rcp_f32_e32 v129, v127
	v_add_f32_e32 v120, 1.0, v120
	v_add_f32_e32 v121, 1.0, v121
	v_rcp_f32_e32 v120, v120
	v_rcp_f32_e32 v121, v121
	s_waitcnt lgkmcnt(0)
	v_add_f32_e32 v144, v144, v145
	v_add_f32_e32 v145, v146, v155
	v_pk_mul_f32 v[116:117], v[116:117], v[156:157] op_sel_hi:[1,0]
	ds_bpermute_b32 v155, v183, v145
	v_pk_mul_f32 v[114:115], v[114:115], v[128:129]
	v_pk_mul_f32 v[116:117], v[118:119], v[116:117]
	v_lshl_add_u32 v126, s72, 8, v181
	v_pk_mul_f32 v[120:121], v[116:117], v[120:121]
	v_cvt_pk_bf16_f32 v118, v114, v115
	v_mov_b64_e32 v[114:115], s[54:55]
	v_cvt_pk_bf16_f32 v119, v120, v121
	v_mad_i64_i32 v[120:121], s[72:73], v126, s65, v[114:115]
	s_lshl_b32 s72, s35, 7
	v_pk_mul_f32 v[122:123], v[122:123], v[162:163]
	s_ashr_i32 s73, s72, 31
	v_lshlrev_b32_e32 v160, 3, v180
	v_cvt_pk_bf16_f32 v116, v122, v123
	s_lshl_b64 s[72:73], s[72:73], 1
	s_waitcnt lgkmcnt(0)
	v_pk_mul_f32 v[122:123], v[110:111], v[154:155] op_sel_hi:[1,0]
	v_ashrrev_i32_e32 v161, 31, v160
	v_pk_mul_f32 v[124:125], v[124:125], v[158:159]
	v_lshl_add_u64 v[120:121], v[120:121], 0, s[72:73]
	v_mul_f32_e32 v110, 0xbfb8aa3b, v122
	v_cvt_pk_bf16_f32 v117, v124, v125
	v_lshl_add_u64 v[120:121], v[120:121], 0, s[48:49]
	v_exp_f32_e32 v124, v110
	v_lshlrev_b64 v[110:111], 1, v[160:161]
	v_lshl_add_u64 v[120:121], v[120:121], 0, v[110:111]
	global_store_dwordx4 v[120:121], v[116:119], off
	v_pk_mul_f32 v[112:113], v[112:113], v[154:155] op_sel_hi:[1,0]
	v_pk_mul_f32 v[106:107], v[106:107], v[154:155] op_sel_hi:[1,0]
	v_mul_f32_e32 v117, 0xbfb8aa3b, v123
	v_exp_f32_e32 v117, v117
	v_add_f32_e32 v116, 1.0, v124
	v_mul_f32_e32 v118, 0xbfb8aa3b, v112
	v_rcp_f32_e32 v116, v116
	v_add_f32_e32 v117, 1.0, v117
	v_rcp_f32_e32 v117, v117
	v_exp_f32_e32 v118, v118
	v_pk_mul_f32 v[106:107], v[122:123], v[106:107]
	v_pk_mul_f32 v[102:103], v[102:103], v[154:155] op_sel_hi:[1,0]
	v_pk_mul_f32 v[108:109], v[108:109], v[154:155] op_sel_hi:[1,0]
	v_mul_f32_e32 v119, 0xbfb8aa3b, v113
	v_pk_mul_f32 v[106:107], v[106:107], v[116:117]
	v_add_f32_e32 v116, 1.0, v118
	v_mul_f32_e32 v118, 0xbfb8aa3b, v102
	v_pk_mul_f32 v[108:109], v[112:113], v[108:109]
	v_mul_f32_e32 v113, 0xbfb8aa3b, v103
	v_pk_mul_f32 v[98:99], v[98:99], v[154:155] op_sel_hi:[1,0]
	v_exp_f32_e32 v118, v118
	v_exp_f32_e32 v113, v113
	v_pk_mul_f32 v[98:99], v[102:103], v[98:99]
	v_pk_mul_f32 v[102:103], v[104:105], v[154:155] op_sel_hi:[1,0]
	v_add_f32_e32 v112, 1.0, v118
	v_mul_f32_e32 v104, 0xbfb8aa3b, v102
	v_mul_f32_e32 v105, 0xbfb8aa3b, v103
	v_exp_f32_e32 v104, v104
	v_exp_f32_e32 v105, v105
	v_add_f32_e32 v113, 1.0, v113
	v_exp_f32_e32 v119, v119
	v_rcp_f32_e32 v112, v112
	v_rcp_f32_e32 v113, v113
	v_add_f32_e32 v104, 1.0, v104
	v_add_f32_e32 v105, 1.0, v105
	v_rcp_f32_e32 v104, v104
	v_rcp_f32_e32 v105, v105
	v_add_f32_e32 v117, 1.0, v119
	v_pk_mul_f32 v[112:113], v[98:99], v[112:113]
	v_pk_mul_f32 v[98:99], v[100:101], v[154:155] op_sel_hi:[1,0]
	v_rcp_f32_e32 v116, v116
	v_rcp_f32_e32 v117, v117
	v_pk_mul_f32 v[98:99], v[102:103], v[98:99]
	v_cvt_pk_bf16_f32 v100, v112, v113
	v_pk_mul_f32 v[102:103], v[98:99], v[104:105]
	v_add_u32_e32 v104, 16, v126
	v_cvt_pk_bf16_f32 v101, v102, v103
	v_mad_i64_i32 v[102:103], s[74:75], v104, s65, v[114:115]
	v_lshl_add_u64 v[102:103], v[102:103], 0, s[72:73]
	v_pk_mul_f32 v[108:109], v[108:109], v[116:117]
	v_lshl_add_u64 v[102:103], v[102:103], 0, s[48:49]
	v_cvt_pk_bf16_f32 v98, v106, v107
	v_cvt_pk_bf16_f32 v99, v108, v109
	v_pk_mul_f32 v[92:93], v[92:93], v[152:153] op_sel_hi:[1,0]
	v_lshl_add_u64 v[102:103], v[102:103], 0, v[110:111]
	v_mul_f32_e32 v104, 0xbfb8aa3b, v92
	global_store_dwordx4 v[102:103], v[98:101], off
	v_exp_f32_e32 v104, v104
	v_pk_mul_f32 v[88:89], v[88:89], v[152:153] op_sel_hi:[1,0]
	v_mul_f32_e32 v99, 0xbfb8aa3b, v93
	v_exp_f32_e32 v99, v99
	v_add_f32_e32 v98, 1.0, v104
	v_pk_mul_f32 v[88:89], v[92:93], v[88:89]
	v_rcp_f32_e32 v98, v98
	v_add_f32_e32 v92, 1.0, v99
	v_rcp_f32_e32 v99, v92
	v_pk_mul_f32 v[92:93], v[94:95], v[152:153] op_sel_hi:[1,0]
	v_pk_mul_f32 v[84:85], v[84:85], v[152:153] op_sel_hi:[1,0]
	v_pk_mul_f32 v[90:91], v[90:91], v[152:153] op_sel_hi:[1,0]
	v_mul_f32_e32 v95, 0xbfb8aa3b, v93
	v_pk_mul_f32 v[88:89], v[88:89], v[98:99]
	v_mul_f32_e32 v98, 0xbfb8aa3b, v84
	v_pk_mul_f32 v[90:91], v[92:93], v[90:91]
	v_mul_f32_e32 v93, 0xbfb8aa3b, v85
	v_pk_mul_f32 v[80:81], v[80:81], v[152:153] op_sel_hi:[1,0]
	v_exp_f32_e32 v98, v98
	v_exp_f32_e32 v93, v93
	v_pk_mul_f32 v[80:81], v[84:85], v[80:81]
	v_pk_mul_f32 v[84:85], v[86:87], v[152:153] op_sel_hi:[1,0]
	v_mul_f32_e32 v94, 0xbfb8aa3b, v92
	v_mul_f32_e32 v86, 0xbfb8aa3b, v84
	v_mul_f32_e32 v87, 0xbfb8aa3b, v85
	v_exp_f32_e32 v86, v86
	v_exp_f32_e32 v87, v87
	v_add_f32_e32 v92, 1.0, v98
	v_add_f32_e32 v93, 1.0, v93
	v_exp_f32_e32 v94, v94
	v_exp_f32_e32 v95, v95
	v_rcp_f32_e32 v92, v92
	v_rcp_f32_e32 v93, v93
	v_add_f32_e32 v86, 1.0, v86
	v_add_f32_e32 v87, 1.0, v87
	v_rcp_f32_e32 v86, v86
	v_rcp_f32_e32 v87, v87
	v_add_f32_e32 v94, 1.0, v94
	v_add_f32_e32 v95, 1.0, v95
	v_pk_mul_f32 v[92:93], v[80:81], v[92:93]
	v_pk_mul_f32 v[80:81], v[82:83], v[152:153] op_sel_hi:[1,0]
	v_rcp_f32_e32 v94, v94
	v_rcp_f32_e32 v95, v95
	v_pk_mul_f32 v[80:81], v[84:85], v[80:81]
	v_cvt_pk_bf16_f32 v82, v92, v93
	v_pk_mul_f32 v[84:85], v[80:81], v[86:87]
	v_add_u32_e32 v86, 32, v126
	v_cvt_pk_bf16_f32 v83, v84, v85
	v_mad_i64_i32 v[84:85], s[74:75], v86, s65, v[114:115]
	v_lshl_add_u64 v[84:85], v[84:85], 0, s[72:73]
	v_pk_mul_f32 v[90:91], v[90:91], v[94:95]
	v_lshl_add_u64 v[84:85], v[84:85], 0, s[48:49]
	v_cvt_pk_bf16_f32 v80, v88, v89
	v_cvt_pk_bf16_f32 v81, v90, v91
	v_pk_mul_f32 v[76:77], v[76:77], v[150:151] op_sel_hi:[1,0]
	v_lshl_add_u64 v[84:85], v[84:85], 0, v[110:111]
	v_mul_f32_e32 v86, 0xbfb8aa3b, v76
	global_store_dwordx4 v[84:85], v[80:83], off
	v_exp_f32_e32 v86, v86
	v_pk_mul_f32 v[72:73], v[72:73], v[150:151] op_sel_hi:[1,0]
	v_mul_f32_e32 v81, 0xbfb8aa3b, v77
	v_exp_f32_e32 v81, v81
	v_add_f32_e32 v80, 1.0, v86
	v_pk_mul_f32 v[72:73], v[76:77], v[72:73]
	v_rcp_f32_e32 v80, v80
	v_add_f32_e32 v76, 1.0, v81
	v_rcp_f32_e32 v81, v76
	v_pk_mul_f32 v[76:77], v[78:79], v[150:151] op_sel_hi:[1,0]
	v_pk_mul_f32 v[68:69], v[68:69], v[150:151] op_sel_hi:[1,0]
	v_pk_mul_f32 v[74:75], v[74:75], v[150:151] op_sel_hi:[1,0]
	v_mul_f32_e32 v79, 0xbfb8aa3b, v77
	v_pk_mul_f32 v[72:73], v[72:73], v[80:81]
	v_mul_f32_e32 v80, 0xbfb8aa3b, v68
	v_pk_mul_f32 v[74:75], v[76:77], v[74:75]
	v_mul_f32_e32 v77, 0xbfb8aa3b, v69
	v_pk_mul_f32 v[64:65], v[64:65], v[150:151] op_sel_hi:[1,0]
	v_exp_f32_e32 v80, v80
	v_exp_f32_e32 v77, v77
	v_pk_mul_f32 v[64:65], v[68:69], v[64:65]
	v_pk_mul_f32 v[68:69], v[70:71], v[150:151] op_sel_hi:[1,0]
	v_mul_f32_e32 v78, 0xbfb8aa3b, v76
	v_mul_f32_e32 v70, 0xbfb8aa3b, v68
	v_mul_f32_e32 v71, 0xbfb8aa3b, v69
	v_exp_f32_e32 v70, v70
	v_exp_f32_e32 v71, v71
	v_add_f32_e32 v76, 1.0, v80
	v_add_f32_e32 v77, 1.0, v77
	v_exp_f32_e32 v78, v78
	v_exp_f32_e32 v79, v79
	v_rcp_f32_e32 v76, v76
	v_rcp_f32_e32 v77, v77
	v_add_f32_e32 v70, 1.0, v70
	v_add_f32_e32 v71, 1.0, v71
	v_rcp_f32_e32 v70, v70
	v_rcp_f32_e32 v71, v71
	v_add_f32_e32 v78, 1.0, v78
	v_add_f32_e32 v79, 1.0, v79
	v_pk_mul_f32 v[76:77], v[64:65], v[76:77]
	v_pk_mul_f32 v[64:65], v[66:67], v[150:151] op_sel_hi:[1,0]
	v_rcp_f32_e32 v78, v78
	v_rcp_f32_e32 v79, v79
	v_pk_mul_f32 v[64:65], v[68:69], v[64:65]
	v_cvt_pk_bf16_f32 v66, v76, v77
	v_pk_mul_f32 v[68:69], v[64:65], v[70:71]
	v_add_u32_e32 v70, 48, v126
	v_cvt_pk_bf16_f32 v67, v68, v69
	v_mad_i64_i32 v[68:69], s[74:75], v70, s65, v[114:115]
	v_lshl_add_u64 v[68:69], v[68:69], 0, s[72:73]
	v_pk_mul_f32 v[74:75], v[74:75], v[78:79]
	v_lshl_add_u64 v[68:69], v[68:69], 0, s[48:49]
	v_cvt_pk_bf16_f32 v64, v72, v73
	v_cvt_pk_bf16_f32 v65, v74, v75
	v_pk_mul_f32 v[60:61], v[60:61], v[148:149] op_sel_hi:[1,0]
	v_lshl_add_u64 v[68:69], v[68:69], 0, v[110:111]
	v_mul_f32_e32 v70, 0xbfb8aa3b, v60
	global_store_dwordx4 v[68:69], v[64:67], off
	v_exp_f32_e32 v70, v70
	v_pk_mul_f32 v[56:57], v[56:57], v[148:149] op_sel_hi:[1,0]
	v_mul_f32_e32 v65, 0xbfb8aa3b, v61
	v_exp_f32_e32 v65, v65
	v_add_f32_e32 v64, 1.0, v70
	v_pk_mul_f32 v[56:57], v[60:61], v[56:57]
	v_rcp_f32_e32 v64, v64
	v_add_f32_e32 v60, 1.0, v65
	v_rcp_f32_e32 v65, v60
	v_pk_mul_f32 v[60:61], v[62:63], v[148:149] op_sel_hi:[1,0]
	v_pk_mul_f32 v[52:53], v[52:53], v[148:149] op_sel_hi:[1,0]
	v_pk_mul_f32 v[58:59], v[58:59], v[148:149] op_sel_hi:[1,0]
	v_mul_f32_e32 v63, 0xbfb8aa3b, v61
	v_pk_mul_f32 v[56:57], v[56:57], v[64:65]
	v_mul_f32_e32 v64, 0xbfb8aa3b, v52
	v_pk_mul_f32 v[58:59], v[60:61], v[58:59]
	v_mul_f32_e32 v61, 0xbfb8aa3b, v53
	v_pk_mul_f32 v[48:49], v[48:49], v[148:149] op_sel_hi:[1,0]
	v_exp_f32_e32 v64, v64
	v_exp_f32_e32 v61, v61
	v_pk_mul_f32 v[48:49], v[52:53], v[48:49]
	v_pk_mul_f32 v[52:53], v[54:55], v[148:149] op_sel_hi:[1,0]
	v_mul_f32_e32 v62, 0xbfb8aa3b, v60
	v_mul_f32_e32 v54, 0xbfb8aa3b, v52
	v_mul_f32_e32 v55, 0xbfb8aa3b, v53
	v_exp_f32_e32 v54, v54
	v_exp_f32_e32 v55, v55
	v_add_f32_e32 v60, 1.0, v64
	v_add_f32_e32 v61, 1.0, v61
	v_exp_f32_e32 v62, v62
	v_exp_f32_e32 v63, v63
	v_rcp_f32_e32 v60, v60
	v_rcp_f32_e32 v61, v61
	v_add_f32_e32 v54, 1.0, v54
	v_add_f32_e32 v55, 1.0, v55
	v_rcp_f32_e32 v54, v54
	v_rcp_f32_e32 v55, v55
	v_add_f32_e32 v62, 1.0, v62
	v_add_f32_e32 v63, 1.0, v63
	v_pk_mul_f32 v[60:61], v[48:49], v[60:61]
	v_pk_mul_f32 v[48:49], v[50:51], v[148:149] op_sel_hi:[1,0]
	v_fmamk_f32 v144, v144, 0x3a800000, v226
	v_rcp_f32_e32 v62, v62
	v_rcp_f32_e32 v63, v63
	v_pk_mul_f32 v[48:49], v[52:53], v[48:49]
	v_rsq_f32_e32 v146, v144
	v_add_u32_e32 v66, 0x80, v126
	v_pk_mul_f32 v[52:53], v[48:49], v[54:55]
	v_pk_mul_f32 v[58:59], v[58:59], v[62:63]
	v_cvt_pk_bf16_f32 v51, v52, v53
	v_mad_i64_i32 v[52:53], s[74:75], v66, s65, v[114:115]
	v_lshl_add_u64 v[52:53], v[52:53], 0, s[72:73]
	v_lshl_add_u64 v[52:53], v[52:53], 0, s[48:49]
	v_cvt_pk_bf16_f32 v48, v56, v57
	v_cvt_pk_bf16_f32 v49, v58, v59
	v_cvt_pk_bf16_f32 v50, v60, v61
	v_pk_mul_f32 v[44:45], v[44:45], v[146:147] op_sel_hi:[1,0]
	v_lshl_add_u64 v[52:53], v[52:53], 0, v[110:111]
	v_mul_f32_e32 v54, 0xbfb8aa3b, v44
	global_store_dwordx4 v[52:53], v[48:51], off
	v_exp_f32_e32 v54, v54
	v_pk_mul_f32 v[40:41], v[40:41], v[146:147] op_sel_hi:[1,0]
	v_mul_f32_e32 v49, 0xbfb8aa3b, v45
	v_exp_f32_e32 v49, v49
	v_add_f32_e32 v48, 1.0, v54
	v_pk_mul_f32 v[40:41], v[44:45], v[40:41]
	v_rcp_f32_e32 v48, v48
	v_add_f32_e32 v44, 1.0, v49
	v_rcp_f32_e32 v49, v44
	v_pk_mul_f32 v[44:45], v[46:47], v[146:147] op_sel_hi:[1,0]
	v_pk_mul_f32 v[36:37], v[36:37], v[146:147] op_sel_hi:[1,0]
	v_pk_mul_f32 v[42:43], v[42:43], v[146:147] op_sel_hi:[1,0]
	v_mul_f32_e32 v47, 0xbfb8aa3b, v45
	v_pk_mul_f32 v[40:41], v[40:41], v[48:49]
	v_mul_f32_e32 v48, 0xbfb8aa3b, v36
	v_pk_mul_f32 v[42:43], v[44:45], v[42:43]
	v_mul_f32_e32 v45, 0xbfb8aa3b, v37
	v_pk_mul_f32 v[32:33], v[32:33], v[146:147] op_sel_hi:[1,0]
	v_exp_f32_e32 v48, v48
	v_exp_f32_e32 v45, v45
	v_pk_mul_f32 v[32:33], v[36:37], v[32:33]
	v_pk_mul_f32 v[36:37], v[38:39], v[146:147] op_sel_hi:[1,0]
	v_mul_f32_e32 v46, 0xbfb8aa3b, v44
	v_mul_f32_e32 v38, 0xbfb8aa3b, v36
	v_mul_f32_e32 v39, 0xbfb8aa3b, v37
	v_exp_f32_e32 v38, v38
	v_exp_f32_e32 v39, v39
	v_add_f32_e32 v44, 1.0, v48
	v_add_f32_e32 v45, 1.0, v45
	v_exp_f32_e32 v46, v46
	v_exp_f32_e32 v47, v47
	v_rcp_f32_e32 v44, v44
	v_rcp_f32_e32 v45, v45
	v_add_f32_e32 v38, 1.0, v38
	v_add_f32_e32 v39, 1.0, v39
	v_rcp_f32_e32 v38, v38
	v_rcp_f32_e32 v39, v39
	v_add_f32_e32 v144, v145, v155
	v_add_f32_e32 v46, 1.0, v46
	v_add_f32_e32 v47, 1.0, v47
	v_pk_mul_f32 v[44:45], v[32:33], v[44:45]
	v_pk_mul_f32 v[32:33], v[34:35], v[146:147] op_sel_hi:[1,0]
	v_fmamk_f32 v144, v144, 0x3a800000, v226
	v_rcp_f32_e32 v46, v46
	v_rcp_f32_e32 v47, v47
	v_pk_mul_f32 v[32:33], v[36:37], v[32:33]
	v_rsq_f32_e32 v144, v144
	v_pk_mul_f32 v[36:37], v[32:33], v[38:39]
	v_add_u32_e32 v38, 0x90, v126
	v_cvt_pk_bf16_f32 v35, v36, v37
	v_mad_i64_i32 v[36:37], s[74:75], v38, s65, v[114:115]
	v_lshl_add_u64 v[36:37], v[36:37], 0, s[72:73]
	v_pk_mul_f32 v[42:43], v[42:43], v[46:47]
	v_lshl_add_u64 v[36:37], v[36:37], 0, s[48:49]
	v_cvt_pk_bf16_f32 v32, v40, v41
	v_cvt_pk_bf16_f32 v33, v42, v43
	v_cvt_pk_bf16_f32 v34, v44, v45
	v_pk_mul_f32 v[28:29], v[28:29], v[144:145] op_sel_hi:[1,0]
	v_lshl_add_u64 v[36:37], v[36:37], 0, v[110:111]
	v_mul_f32_e32 v38, 0xbfb8aa3b, v28
	global_store_dwordx4 v[36:37], v[32:35], off
	v_exp_f32_e32 v38, v38
	v_pk_mul_f32 v[24:25], v[24:25], v[144:145] op_sel_hi:[1,0]
	v_mul_f32_e32 v33, 0xbfb8aa3b, v29
	v_exp_f32_e32 v33, v33
	v_add_f32_e32 v32, 1.0, v38
	v_pk_mul_f32 v[24:25], v[28:29], v[24:25]
	v_rcp_f32_e32 v32, v32
	v_add_f32_e32 v28, 1.0, v33
	v_rcp_f32_e32 v33, v28
	v_pk_mul_f32 v[28:29], v[30:31], v[144:145] op_sel_hi:[1,0]
	v_pk_mul_f32 v[20:21], v[20:21], v[144:145] op_sel_hi:[1,0]
	v_pk_mul_f32 v[26:27], v[26:27], v[144:145] op_sel_hi:[1,0]
	v_mul_f32_e32 v31, 0xbfb8aa3b, v29
	v_pk_mul_f32 v[24:25], v[24:25], v[32:33]
	v_mul_f32_e32 v32, 0xbfb8aa3b, v20
	v_pk_mul_f32 v[26:27], v[28:29], v[26:27]
	v_mul_f32_e32 v29, 0xbfb8aa3b, v21
	v_pk_mul_f32 v[16:17], v[16:17], v[144:145] op_sel_hi:[1,0]
	v_exp_f32_e32 v32, v32
	v_exp_f32_e32 v29, v29
	v_pk_mul_f32 v[16:17], v[20:21], v[16:17]
	v_pk_mul_f32 v[20:21], v[22:23], v[144:145] op_sel_hi:[1,0]
	v_mul_f32_e32 v30, 0xbfb8aa3b, v28
	v_mul_f32_e32 v22, 0xbfb8aa3b, v20
	v_mul_f32_e32 v23, 0xbfb8aa3b, v21
	v_exp_f32_e32 v22, v22
	v_exp_f32_e32 v23, v23
	v_add_f32_e32 v28, 1.0, v32
	v_add_f32_e32 v29, 1.0, v29
	v_exp_f32_e32 v30, v30
	v_exp_f32_e32 v31, v31
	v_rcp_f32_e32 v28, v28
	v_rcp_f32_e32 v29, v29
	v_add_f32_e32 v22, 1.0, v22
	v_add_f32_e32 v23, 1.0, v23
	v_rcp_f32_e32 v22, v22
	v_rcp_f32_e32 v23, v23
	v_add_f32_e32 v30, 1.0, v30
	v_add_f32_e32 v31, 1.0, v31
	v_pk_mul_f32 v[28:29], v[16:17], v[28:29]
	v_pk_mul_f32 v[16:17], v[18:19], v[144:145] op_sel_hi:[1,0]
	v_fmamk_f32 v142, v142, 0x3a800000, v226
	v_rcp_f32_e32 v30, v30
	v_rcp_f32_e32 v31, v31
	v_pk_mul_f32 v[16:17], v[20:21], v[16:17]
	v_rsq_f32_e32 v142, v142
	v_pk_mul_f32 v[20:21], v[16:17], v[22:23]
	v_add_u32_e32 v22, 0xa0, v126
	v_cvt_pk_bf16_f32 v19, v20, v21
	v_mad_i64_i32 v[20:21], s[74:75], v22, s65, v[114:115]
	v_lshl_add_u64 v[20:21], v[20:21], 0, s[72:73]
	v_pk_mul_f32 v[26:27], v[26:27], v[30:31]
	v_lshl_add_u64 v[20:21], v[20:21], 0, s[48:49]
	v_cvt_pk_bf16_f32 v16, v24, v25
	v_cvt_pk_bf16_f32 v17, v26, v27
	v_cvt_pk_bf16_f32 v18, v28, v29
	v_pk_mul_f32 v[12:13], v[12:13], v[142:143] op_sel_hi:[1,0]
	v_lshl_add_u64 v[20:21], v[20:21], 0, v[110:111]
	v_mul_f32_e32 v22, 0xbfb8aa3b, v12
	global_store_dwordx4 v[20:21], v[16:19], off
	v_exp_f32_e32 v22, v22
	v_pk_mul_f32 v[8:9], v[8:9], v[142:143] op_sel_hi:[1,0]
	v_mul_f32_e32 v17, 0xbfb8aa3b, v13
	v_exp_f32_e32 v17, v17
	v_add_f32_e32 v16, 1.0, v22
	v_pk_mul_f32 v[8:9], v[12:13], v[8:9]
	v_rcp_f32_e32 v16, v16
	v_add_f32_e32 v12, 1.0, v17
	v_rcp_f32_e32 v17, v12
	v_pk_mul_f32 v[12:13], v[14:15], v[142:143] op_sel_hi:[1,0]
	v_pk_mul_f32 v[4:5], v[4:5], v[142:143] op_sel_hi:[1,0]
	v_pk_mul_f32 v[10:11], v[10:11], v[142:143] op_sel_hi:[1,0]
	v_mul_f32_e32 v15, 0xbfb8aa3b, v13
	v_pk_mul_f32 v[8:9], v[8:9], v[16:17]
	v_mul_f32_e32 v16, 0xbfb8aa3b, v4
	v_pk_mul_f32 v[10:11], v[12:13], v[10:11]
	v_mul_f32_e32 v13, 0xbfb8aa3b, v5
	v_pk_mul_f32 v[0:1], v[0:1], v[142:143] op_sel_hi:[1,0]
	v_exp_f32_e32 v16, v16
	v_exp_f32_e32 v13, v13
	v_pk_mul_f32 v[0:1], v[4:5], v[0:1]
	v_pk_mul_f32 v[4:5], v[6:7], v[142:143] op_sel_hi:[1,0]
	v_mul_f32_e32 v14, 0xbfb8aa3b, v12
	v_mul_f32_e32 v6, 0xbfb8aa3b, v4
	v_mul_f32_e32 v7, 0xbfb8aa3b, v5
	v_exp_f32_e32 v6, v6
	v_exp_f32_e32 v7, v7
	v_add_f32_e32 v12, 1.0, v16
	v_add_f32_e32 v13, 1.0, v13
	v_exp_f32_e32 v14, v14
	v_exp_f32_e32 v15, v15
	v_rcp_f32_e32 v12, v12
	v_rcp_f32_e32 v13, v13
	v_add_f32_e32 v6, 1.0, v6
	v_add_f32_e32 v7, 1.0, v7
	v_rcp_f32_e32 v6, v6
	v_rcp_f32_e32 v7, v7
	v_add_f32_e32 v14, 1.0, v14
	v_add_f32_e32 v15, 1.0, v15
	v_pk_mul_f32 v[12:13], v[0:1], v[12:13]
	v_pk_mul_f32 v[0:1], v[2:3], v[142:143] op_sel_hi:[1,0]
	v_rcp_f32_e32 v14, v14
	v_rcp_f32_e32 v15, v15
	v_pk_mul_f32 v[0:1], v[4:5], v[0:1]
	v_cvt_pk_bf16_f32 v2, v12, v13
	v_pk_mul_f32 v[4:5], v[0:1], v[6:7]
	v_add_u32_e32 v6, 0xb0, v126
	v_cvt_pk_bf16_f32 v3, v4, v5
	v_mad_i64_i32 v[4:5], s[74:75], v6, s65, v[114:115]
	v_lshl_add_u64 v[4:5], v[4:5], 0, s[72:73]
	v_pk_mul_f32 v[10:11], v[10:11], v[14:15]
	v_lshl_add_u64 v[4:5], v[4:5], 0, s[48:49]
	v_cvt_pk_bf16_f32 v0, v8, v9
	v_cvt_pk_bf16_f32 v1, v10, v11
	v_lshl_add_u64 v[4:5], v[4:5], 0, v[110:111]
	s_mov_b64 s[6:7], -1
	global_store_dwordx4 v[4:5], v[0:3], off
	s_cbranch_vccnz .LBB0_151
	s_andn2_b64 vcc, exec, s[52:53]
	s_cbranch_vccnz .LBB0_150
	s_barrier
	s_branch .LBB0_150

.LBB0_436:
	s_or_b64 exec, exec, s[70:71]
	v_lshlrev_b32_e32 v98, 16, v142
	s_waitcnt lgkmcnt(0)
	v_and_b32_e32 v99, 0xffff0000, v142
	v_pk_fma_f32 v[92:93], v[92:93], 0.5, v[98:99] op_sel_hi:[1,0,1]
	v_lshlrev_b32_e32 v98, 16, v143
	v_and_b32_e32 v99, 0xffff0000, v143
	v_pk_fma_f32 v[94:95], v[94:95], 0.5, v[98:99] op_sel_hi:[1,0,1]
	v_lshlrev_b32_e32 v98, 16, v144
	v_and_b32_e32 v99, 0xffff0000, v144
	v_pk_fma_f32 v[98:99], v[88:89], 0.5, v[98:99] op_sel_hi:[1,0,1]
	v_lshlrev_b32_e32 v88, 16, v145
	v_and_b32_e32 v89, 0xffff0000, v145
	v_pk_fma_f32 v[100:101], v[90:91], 0.5, v[88:89] op_sel_hi:[1,0,1]
	v_cvt_pk_bf16_f32 v88, v92, v93
	v_and_b32_e32 v93, 0xffff0000, v88
	v_cvt_pk_bf16_f32 v89, v94, v95
	v_lshlrev_b32_e32 v92, 16, v88
	v_mul_f32_e32 v102, v93, v93
	v_lshlrev_b32_e32 v94, 16, v89
	v_fmac_f32_e32 v102, v92, v92
	v_cvt_pk_bf16_f32 v90, v98, v99
	v_and_b32_e32 v95, 0xffff0000, v89
	v_fmac_f32_e32 v102, v94, v94
	v_lshlrev_b32_e32 v92, 16, v138
	v_and_b32_e32 v93, 0xffff0000, v138
	v_lshlrev_b32_e32 v98, 16, v90
	v_fmac_f32_e32 v102, v95, v95
	v_pk_fma_f32 v[84:85], v[84:85], 0.5, v[92:93] op_sel_hi:[1,0,1]
	v_lshlrev_b32_e32 v92, 16, v139
	v_and_b32_e32 v93, 0xffff0000, v139
	v_cvt_pk_bf16_f32 v91, v100, v101
	v_and_b32_e32 v99, 0xffff0000, v90
	v_fmac_f32_e32 v102, v98, v98
	v_pk_fma_f32 v[86:87], v[86:87], 0.5, v[92:93] op_sel_hi:[1,0,1]
	v_lshlrev_b32_e32 v92, 16, v140
	v_and_b32_e32 v93, 0xffff0000, v140
	v_lshlrev_b32_e32 v100, 16, v91
	v_fmac_f32_e32 v102, v99, v99
	v_pk_fma_f32 v[80:81], v[80:81], 0.5, v[92:93] op_sel_hi:[1,0,1]
	v_lshlrev_b32_e32 v92, 16, v141
	v_and_b32_e32 v93, 0xffff0000, v141
	v_and_b32_e32 v101, 0xffff0000, v91
	v_fmac_f32_e32 v102, v100, v100
	v_pk_fma_f32 v[92:93], v[82:83], 0.5, v[92:93] op_sel_hi:[1,0,1]
	v_cvt_pk_bf16_f32 v82, v84, v85
	v_fmac_f32_e32 v102, v101, v101
	v_cvt_pk_bf16_f32 v84, v80, v81
	v_lshlrev_b32_e32 v80, 16, v82
	v_cvt_pk_bf16_f32 v83, v86, v87
	v_and_b32_e32 v81, 0xffff0000, v82
	v_fmac_f32_e32 v102, v80, v80
	v_lshlrev_b32_e32 v86, 16, v83
	v_fmac_f32_e32 v102, v81, v81
	v_and_b32_e32 v87, 0xffff0000, v83
	v_fmac_f32_e32 v102, v86, v86
	v_cvt_pk_bf16_f32 v85, v92, v93
	v_lshlrev_b32_e32 v92, 16, v84
	v_fmac_f32_e32 v102, v87, v87
	v_and_b32_e32 v93, 0xffff0000, v84
	v_fmac_f32_e32 v102, v92, v92
	v_lshlrev_b32_e32 v94, 16, v85
	v_fmac_f32_e32 v102, v93, v93
	v_and_b32_e32 v95, 0xffff0000, v85
	v_fmac_f32_e32 v102, v94, v94
	v_fmac_f32_e32 v102, v95, v95
	v_mov_b32_e32 v80, v102
	s_nop 1
	v_permlane16_swap_b32_e32 v80, v102
	v_lshl_add_u64 v[86:87], s[50:51], 0, v[180:181]
	v_lshl_add_u64 v[86:87], v[168:169], 1, v[86:87]
	global_store_dwordx4 v[86:87], v[88:91], off
	global_store_dwordx4 v[86:87], v[82:85], off offset:256
	s_waitcnt lgkmcnt(0)
	v_add_f32_e32 v80, v102, v80
	ds_bpermute_b32 v81, v191, v80
	s_and_saveexec_b64 s[70:71], vcc
	s_cbranch_execz .LBB0_438
	s_waitcnt lgkmcnt(0)
	v_add_f32_e32 v82, v80, v81
	s_lshl_b32 s22, s44, 2
	v_lshlrev_b64 v[80:81], 6, v[178:179]
	s_ashr_i32 s23, s22, 31
	v_lshl_add_u64 v[80:81], s[52:53], 0, v[80:81]
	v_lshl_add_u64 v[80:81], s[22:23], 2, v[80:81]
	s_lshl_b32 s48, s78, 2
	v_lshl_add_u64 v[80:81], v[80:81], 0, s[48:49]
	global_store_dword v[80:81], v82, off
.LBB0_438:
	s_or_b64 exec, exec, s[70:71]
	v_lshlrev_b32_e32 v80, 16, v134
	s_waitcnt lgkmcnt(0)
	v_and_b32_e32 v81, 0xffff0000, v134
	v_pk_fma_f32 v[76:77], v[76:77], 0.5, v[80:81] op_sel_hi:[1,0,1]
	v_lshlrev_b32_e32 v80, 16, v135
	v_and_b32_e32 v81, 0xffff0000, v135
	v_pk_fma_f32 v[78:79], v[78:79], 0.5, v[80:81] op_sel_hi:[1,0,1]
	v_lshlrev_b32_e32 v80, 16, v136
	v_and_b32_e32 v81, 0xffff0000, v136
	v_pk_fma_f32 v[80:81], v[72:73], 0.5, v[80:81] op_sel_hi:[1,0,1]
	v_lshlrev_b32_e32 v72, 16, v137
	v_and_b32_e32 v73, 0xffff0000, v137
	v_pk_fma_f32 v[82:83], v[74:75], 0.5, v[72:73] op_sel_hi:[1,0,1]
	v_cvt_pk_bf16_f32 v72, v76, v77
	v_and_b32_e32 v77, 0xffff0000, v72
	v_cvt_pk_bf16_f32 v73, v78, v79
	v_lshlrev_b32_e32 v76, 16, v72
	v_mul_f32_e32 v84, v77, v77
	v_lshlrev_b32_e32 v78, 16, v73
	v_fmac_f32_e32 v84, v76, v76
	v_cvt_pk_bf16_f32 v74, v80, v81
	v_and_b32_e32 v79, 0xffff0000, v73
	v_fmac_f32_e32 v84, v78, v78
	v_lshlrev_b32_e32 v76, 16, v130
	v_and_b32_e32 v77, 0xffff0000, v130
	v_lshlrev_b32_e32 v80, 16, v74
	v_fmac_f32_e32 v84, v79, v79
	v_pk_fma_f32 v[68:69], v[68:69], 0.5, v[76:77] op_sel_hi:[1,0,1]
	v_lshlrev_b32_e32 v76, 16, v131
	v_and_b32_e32 v77, 0xffff0000, v131
	v_cvt_pk_bf16_f32 v75, v82, v83
	v_and_b32_e32 v81, 0xffff0000, v74
	v_fmac_f32_e32 v84, v80, v80
	v_pk_fma_f32 v[70:71], v[70:71], 0.5, v[76:77] op_sel_hi:[1,0,1]
	v_lshlrev_b32_e32 v76, 16, v132
	v_and_b32_e32 v77, 0xffff0000, v132
	v_lshlrev_b32_e32 v82, 16, v75
	v_fmac_f32_e32 v84, v81, v81
	v_pk_fma_f32 v[64:65], v[64:65], 0.5, v[76:77] op_sel_hi:[1,0,1]
	v_lshlrev_b32_e32 v76, 16, v133
	v_and_b32_e32 v77, 0xffff0000, v133
	v_and_b32_e32 v83, 0xffff0000, v75
	v_fmac_f32_e32 v84, v82, v82
	v_pk_fma_f32 v[76:77], v[66:67], 0.5, v[76:77] op_sel_hi:[1,0,1]
	v_cvt_pk_bf16_f32 v66, v68, v69
	v_fmac_f32_e32 v84, v83, v83
	v_cvt_pk_bf16_f32 v68, v64, v65
	v_lshlrev_b32_e32 v64, 16, v66
	v_cvt_pk_bf16_f32 v67, v70, v71
	v_and_b32_e32 v65, 0xffff0000, v66
	v_fmac_f32_e32 v84, v64, v64
	v_lshlrev_b32_e32 v70, 16, v67
	v_fmac_f32_e32 v84, v65, v65
	v_and_b32_e32 v71, 0xffff0000, v67
	v_fmac_f32_e32 v84, v70, v70
	v_cvt_pk_bf16_f32 v69, v76, v77
	v_lshlrev_b32_e32 v76, 16, v68
	v_fmac_f32_e32 v84, v71, v71
	v_and_b32_e32 v77, 0xffff0000, v68
	v_fmac_f32_e32 v84, v76, v76
	v_lshlrev_b32_e32 v78, 16, v69
	v_fmac_f32_e32 v84, v77, v77
	v_and_b32_e32 v79, 0xffff0000, v69
	v_fmac_f32_e32 v84, v78, v78
	v_fmac_f32_e32 v84, v79, v79
	v_mov_b32_e32 v64, v84
	s_nop 1
	v_permlane16_swap_b32_e32 v64, v84
	v_lshl_add_u64 v[70:71], s[50:51], 0, v[176:177]
	v_lshl_add_u64 v[70:71], v[168:169], 1, v[70:71]
	global_store_dwordx4 v[70:71], v[72:75], off
	global_store_dwordx4 v[70:71], v[66:69], off offset:256
	s_waitcnt lgkmcnt(0)
	v_add_f32_e32 v64, v84, v64
	ds_bpermute_b32 v65, v191, v64
	s_and_saveexec_b64 s[70:71], vcc
	s_cbranch_execz .LBB0_440
	s_waitcnt lgkmcnt(0)
	v_add_f32_e32 v66, v64, v65
	s_lshl_b32 s22, s44, 2
	v_lshlrev_b64 v[64:65], 6, v[174:175]
	s_ashr_i32 s23, s22, 31
	v_lshl_add_u64 v[64:65], s[52:53], 0, v[64:65]
	v_lshl_add_u64 v[64:65], s[22:23], 2, v[64:65]
	s_lshl_b32 s48, s78, 2
	v_lshl_add_u64 v[64:65], v[64:65], 0, s[48:49]
	global_store_dword v[64:65], v66, off

.LBB0_536:
	v_mov_b32_e32 v96, v189
	v_mov_b32_e32 v145, v188
	v_and_b32_e32 v171, 64, v225
	v_add_u32_e32 v96, s67, v96
	v_lshlrev_b32_e32 v144, 4, v145
	s_add_i32 s1, 0, 0x21000
	v_lshlrev_b32_e32 v146, 6, v96
	v_xor_b32_e32 v170, 16, v225
	v_add_u32_e32 v172, 64, v171
	s_waitcnt vmcnt(16)
	s_barrier
	v_add3_u32 v144, s1, v144, v146
	v_cmp_lt_i32_e32 vcc, v170, v172
	ds_read_b128 v[146:149], v144
	ds_read_b128 v[150:153], v144 offset:1024
	ds_read_b128 v[154:157], v144 offset:2048
	ds_read_b128 v[158:161], v144 offset:3072
	ds_read_b128 v[162:165], v144 offset:8192
	ds_read_b128 v[166:169], v144 offset:9216
	v_cndmask_b32_e32 v170, v225, v170, vcc
	v_lshlrev_b32_e32 v192, 2, v170
	s_waitcnt lgkmcnt(0)
	v_mov_b32_e32 v170, v147
	v_mov_b32_e32 v171, v148
	v_mov_b32_e32 v147, v149
	v_pk_add_f32 v[146:147], v[170:171], v[146:147]
	v_xor_b32_e32 v148, 32, v225
	v_add_f32_e32 v146, v146, v147
	v_mov_b32_e32 v147, v146
	s_nop 1
	v_permlane16_swap_b32_e32 v147, v146
	v_cmp_lt_i32_e32 vcc, v148, v172
	s_lshl_b32 s94, s93, 1
	v_readlane_b32 s1, v249, 47
	v_cndmask_b32_e32 v148, v225, v148, vcc
	v_lshlrev_b32_e32 v193, 2, v148
	s_waitcnt lgkmcnt(0)
	v_add_f32_e32 v170, v146, v147
	v_mov_b32_e32 v171, v170
	s_nop 1
	v_permlane32_swap_b32_e32 v171, v170
	v_add_f32_e32 v146, v150, v151
	v_add_f32_e32 v147, v152, v153
	v_add_f32_e32 v172, v146, v147
	ds_read_b128 v[146:149], v144 offset:10240
	ds_read_b128 v[150:153], v144 offset:11264
	s_waitcnt lgkmcnt(0)
	v_add_f32_e32 v144, v170, v171
	v_fmamk_f32 v144, v144, 0x3a800000, v226
	v_rsq_f32_e32 v170, v144
	v_add_f32_e32 v144, v154, v155
	v_add_f32_e32 v154, v156, v157
	v_add_f32_e32 v144, v144, v154
	v_mov_b32_e32 v154, v144
	s_nop 1
	v_permlane16_swap_b32_e32 v154, v144
	v_add_f32_e32 v155, v158, v159
	v_add_f32_e32 v156, v160, v161
	v_add_f32_e32 v157, v162, v163
	v_add_f32_e32 v158, v164, v165
	s_waitcnt lgkmcnt(0)
	v_add_f32_e32 v206, v144, v154
	v_add_f32_e32 v144, v166, v167
	v_add_f32_e32 v154, v168, v169
	v_add_f32_e32 v146, v146, v147
	v_add_f32_e32 v147, v148, v149
	v_add_f32_e32 v148, v150, v151
	v_add_f32_e32 v149, v152, v153
	v_add_f32_e32 v155, v155, v156
	v_add_f32_e32 v157, v157, v158
	v_add_f32_e32 v144, v144, v154
	v_add_f32_e32 v146, v146, v147
	v_add_f32_e32 v148, v148, v149
	v_mov_b32_e32 v173, v172
	s_nop 1
	v_permlane16_swap_b32_e32 v173, v172
	v_mov_b32_e32 v156, v155
	s_nop 1
	v_permlane16_swap_b32_e32 v156, v155
	v_mov_b32_e32 v158, v157
	s_nop 1
	v_permlane16_swap_b32_e32 v158, v157
	v_mov_b32_e32 v154, v144
	s_nop 1
	v_permlane16_swap_b32_e32 v154, v144
	v_mov_b32_e32 v147, v146
	s_nop 1
	v_permlane16_swap_b32_e32 v147, v146
	v_mov_b32_e32 v149, v148
	s_nop 1
	v_permlane16_swap_b32_e32 v149, v148
	s_waitcnt lgkmcnt(0)
	v_add_f32_e32 v208, v172, v173
	v_add_f32_e32 v204, v155, v156
	v_add_f32_e32 v202, v157, v158
	v_add_f32_e32 v200, v144, v154
	v_add_f32_e32 v198, v146, v147
	v_add_f32_e32 v196, v148, v149
	ds_bpermute_b32 v209, v193, v208
	ds_bpermute_b32 v207, v193, v206
	ds_bpermute_b32 v205, v193, v204
	ds_bpermute_b32 v203, v193, v202
	ds_bpermute_b32 v201, v193, v200
	ds_bpermute_b32 v199, v193, v198
	ds_bpermute_b32 v197, v193, v196
	v_lshl_add_u32 v148, s10, 8, v96
	v_lshlrev_b32_e32 v144, 3, v145
	v_ashrrev_i32_e32 v149, 31, v148
	s_cmp_gt_i32 s93, 2
	v_add_u32_e32 v146, s1, v144
	v_lshlrev_b64 v[152:153], 11, v[148:149]
	v_lshlrev_b64 v[156:157], 10, v[148:149]
	s_cselect_b64 s[12:13], -1, 0
	v_add_u32_e32 v195, 0xfffff300, v146
	v_ashrrev_i32_e32 v147, 31, v146
	v_add_u32_e32 v194, 0xfffffb00, v146
	v_cmp_eq_u32_e64 s[8:9], 0, v145
	v_lshl_add_u64 v[172:173], s[50:51], 0, v[152:153]
	v_lshl_add_u64 v[150:151], s[72:73], 0, v[156:157]
	v_lshl_add_u64 v[154:155], s[52:53], 0, v[152:153]
	v_lshl_add_u64 v[152:153], s[96:97], 0, v[156:157]
	v_pk_mul_f32 v[164:165], v[126:127], v[170:171] op_sel_hi:[1,0]
	v_pk_mul_f32 v[166:167], v[128:129], v[170:171] op_sel_hi:[1,0]
	v_pk_mul_f32 v[168:169], v[122:123], v[170:171] op_sel_hi:[1,0]
	v_pk_mul_f32 v[176:177], v[124:125], v[170:171] op_sel_hi:[1,0]
	s_mov_b64 s[10:11], -1
	s_and_b64 vcc, exec, s[12:13]
	s_cbranch_vccz .LBB0_558
	s_cmp_gt_u32 s94, 9
	s_cbranch_scc0 .LBB0_555
	s_cmp_gt_u32 s94, 13
	s_cbranch_scc0 .LBB0_552
	s_cmp_gt_u32 s94, 17
	s_cbranch_scc0 .LBB0_549
	s_cmp_gt_u32 s94, 21
	s_cbranch_scc0 .LBB0_546
	s_cmp_gt_u32 s94, 25
	s_cbranch_scc0 .LBB0_543
	v_mul_f32_e32 v122, 0xbfb8aa3b, v164
	v_mul_f32_e32 v123, 0xbfb8aa3b, v165
	v_mul_f32_e32 v124, 0xbfb8aa3b, v166
	v_mul_f32_e32 v125, 0xbfb8aa3b, v167
	v_mul_f32_e32 v127, 0xbfb8aa3b, v168
	v_mul_f32_e32 v128, 0xbfb8aa3b, v169
	v_exp_f32_e32 v122, v122
	v_exp_f32_e32 v123, v123
	v_exp_f32_e32 v124, v124
	v_exp_f32_e32 v125, v125
	v_exp_f32_e32 v127, v127
	v_exp_f32_e32 v128, v128
	v_mul_f32_e32 v129, 0xbfb8aa3b, v176
	v_mul_f32_e32 v156, 0xbfb8aa3b, v177
	v_exp_f32_e32 v129, v129
	v_exp_f32_e32 v156, v156
	v_add_f32_e32 v122, 1.0, v122
	v_add_f32_e32 v123, 1.0, v123
	v_add_f32_e32 v124, 1.0, v124
	v_add_f32_e32 v125, 1.0, v125
	v_add_f32_e32 v127, 1.0, v127
	v_add_f32_e32 v128, 1.0, v128
	v_rcp_f32_e32 v122, v122
	v_rcp_f32_e32 v123, v123
	v_rcp_f32_e32 v124, v124
	v_rcp_f32_e32 v125, v125
	v_rcp_f32_e32 v127, v127
	v_rcp_f32_e32 v128, v128
	v_lshl_add_u32 v96, s93, 8, v195
	v_add_f32_e32 v129, 1.0, v129
	v_add_f32_e32 v156, 1.0, v156
	v_ashrrev_i32_e32 v126, 10, v96
	v_rcp_f32_e32 v129, v129
	v_rcp_f32_e32 v156, v156
	v_cvt_pk_bf16_f32 v122, v122, v123
	v_cvt_pk_bf16_f32 v123, v124, v125
	v_cvt_pk_bf16_f32 v124, v127, v128
	v_ashrrev_i32_e32 v127, 31, v126
	v_and_b32_e32 v96, 0x3f8, v96
	v_lshlrev_b64 v[126:127], 25, v[126:127]
	v_lshl_add_u64 v[126:127], v[172:173], 0, v[126:127]
	v_lshlrev_b32_e32 v96, 1, v96
	v_cvt_pk_bf16_f32 v125, v129, v156
	v_lshl_add_u64 v[126:127], v[126:127], 0, v[96:97]
	global_store_dwordx4 v[126:127], v[122:125], off
	s_mov_b64 s[10:11], 0
	s_mov_b64 s[10:11], 0
	s_branch .LBB0_558

.LBB0_558:
	v_readlane_b32 s14, v248, 2
	v_lshlrev_b64 v[122:123], 1, v[146:147]
	v_readlane_b32 s15, v248, 3
	v_lshl_add_u64 v[126:127], s[42:43], 0, v[122:123]
	v_lshlrev_b64 v[174:175], 6, v[148:149]
	v_lshl_add_u64 v[128:129], s[14:15], 0, v[122:123]
	v_lshlrev_b64 v[122:123], 9, v[148:149]
	v_lshl_add_u64 v[162:163], v[126:127], 0, v[122:123]
	v_lshlrev_b64 v[122:123], 5, v[148:149]
	v_lshl_add_u64 v[160:161], s[54:55], 0, v[122:123]
	v_mad_i64_i32 v[158:159], s[14:15], v148, s36, v[128:129]
	s_andn2_b64 vcc, exec, s[10:11]
	v_lshl_add_u64 v[156:157], s[24:25], 0, v[174:175]
	s_cbranch_vccnz .LBB0_567
	v_pk_mul_f32 v[122:123], v[164:165], v[164:165]
	v_pk_mul_f32 v[124:125], v[166:167], v[166:167]
	v_add_f32_e32 v96, v122, v123
	v_add_f32_e32 v96, v124, v96
	v_pk_mul_f32 v[178:179], v[168:169], v[168:169]
	v_add_f32_e32 v96, v125, v96
	v_add_f32_e32 v96, v178, v96
	v_pk_mul_f32 v[180:181], v[176:177], v[176:177]
	v_add_f32_e32 v96, v179, v96
	v_add_f32_e32 v96, v180, v96
	v_add_f32_e32 v96, v181, v96
	v_mov_b32_e32 v122, v96
	s_nop 1
	v_permlane16_swap_b32_e32 v122, v96
	s_cmp_eq_u32 s93, 2
	v_cvt_pk_bf16_f32 v123, v166, v167
	v_cvt_pk_bf16_f32 v124, v168, v169
	v_cvt_pk_bf16_f32 v125, v176, v177
	s_waitcnt lgkmcnt(0)
	v_add_f32_e32 v96, v96, v122
	v_mov_b32_e32 v149, v96
	s_nop 1
	v_permlane32_swap_b32_e32 v149, v96
	v_cvt_pk_bf16_f32 v122, v164, v165
	s_mov_b64 s[10:11], -1
	s_waitcnt lgkmcnt(0)
	v_add_f32_e32 v96, v96, v149
	s_cbranch_scc1 .LBB0_563
	s_lshl_b32 s10, s93, 8
	s_ashr_i32 s11, s10, 31
	v_lshl_add_u64 v[164:165], s[10:11], 1, v[158:159]
	global_store_dwordx4 v[164:165], v[122:125], off
	s_and_saveexec_b64 s[10:11], s[8:9]
	s_cbranch_execz .LBB0_562
	s_lshl_b32 s14, s93, 3
	s_ashr_i32 s15, s14, 31
	v_lshl_add_u64 v[164:165], s[14:15], 2, v[156:157]
	global_store_dword v[164:165], v96, off

.LBB0_594:
	s_andn2_b64 vcc, exec, s[10:11]
	s_cbranch_vccnz .LBB0_603
	v_pk_mul_f32 v[114:115], v[164:165], v[164:165]
	v_pk_mul_f32 v[116:117], v[166:167], v[166:167]
	v_add_f32_e32 v96, v114, v115
	v_add_f32_e32 v96, v116, v96
	v_pk_mul_f32 v[118:119], v[168:169], v[168:169]
	v_add_f32_e32 v96, v117, v96
	v_add_f32_e32 v96, v118, v96
	v_pk_mul_f32 v[120:121], v[170:171], v[170:171]
	v_add_f32_e32 v96, v119, v96
	v_add_f32_e32 v96, v120, v96
	v_add_f32_e32 v96, v121, v96
	v_mov_b32_e32 v114, v96
	s_nop 1
	v_permlane16_swap_b32_e32 v114, v96
	s_cmp_lt_i32 s95, 3
	v_cvt_pk_bf16_f32 v115, v166, v167
	v_cvt_pk_bf16_f32 v116, v168, v169
	v_cvt_pk_bf16_f32 v117, v170, v171
	s_waitcnt lgkmcnt(0)
	v_add_f32_e32 v96, v96, v114
	v_mov_b32_e32 v118, v96
	s_nop 1
	v_permlane32_swap_b32_e32 v118, v96
	v_cvt_pk_bf16_f32 v114, v164, v165
	s_mov_b64 s[10:11], -1
	s_waitcnt lgkmcnt(0)
	v_add_f32_e32 v96, v96, v118
	s_cbranch_scc1 .LBB0_599
	s_add_i32 s1, s94, -2
	s_lshl_b32 s48, s1, 8
	v_lshl_add_u64 v[118:119], v[162:163], 0, s[48:49]
	global_store_dwordx4 v[118:119], v[114:117], off
	s_and_saveexec_b64 s[10:11], s[8:9]
	s_cbranch_execz .LBB0_598
	s_lshl_b32 s48, s1, 2
	v_lshl_add_u64 v[118:119], s[48:49], 2, v[160:161]
	global_store_dword v[118:119], v96, off

.LBB0_625:
	s_nop 0
	v_lshlrev_b64 v[106:107], 9, v[114:115]
	v_lshl_add_u64 v[152:153], v[126:127], 0, v[106:107]
	v_lshlrev_b64 v[106:107], 5, v[114:115]
	v_lshlrev_b64 v[160:161], 6, v[114:115]
	v_lshl_add_u64 v[150:151], s[54:55], 0, v[106:107]
	v_mad_i64_i32 v[112:113], s[22:23], v114, s36, v[128:129]
	s_andn2_b64 vcc, exec, s[12:13]
	v_lshl_add_u64 v[110:111], s[24:25], 0, v[160:161]
	s_cbranch_vccnz .LBB0_634
	v_pk_mul_f32 v[106:107], v[154:155], v[154:155]
	v_pk_mul_f32 v[108:109], v[162:163], v[162:163]
	v_add_f32_e32 v96, v106, v107
	v_add_f32_e32 v96, v108, v96
	v_pk_mul_f32 v[168:169], v[164:165], v[164:165]
	v_add_f32_e32 v96, v109, v96
	v_add_f32_e32 v96, v168, v96
	v_pk_mul_f32 v[170:171], v[166:167], v[166:167]
	v_add_f32_e32 v96, v169, v96
	v_add_f32_e32 v96, v170, v96
	v_add_f32_e32 v96, v171, v96
	v_mov_b32_e32 v106, v96
	s_nop 1
	v_permlane16_swap_b32_e32 v106, v96
	s_cmp_lg_u32 s93, 2
	v_cvt_pk_bf16_f32 v107, v162, v163
	v_cvt_pk_bf16_f32 v108, v164, v165
	v_cvt_pk_bf16_f32 v109, v166, v167
	s_waitcnt lgkmcnt(0)
	v_add_f32_e32 v96, v96, v106
	v_mov_b32_e32 v115, v96
	s_nop 1
	v_permlane32_swap_b32_e32 v115, v96
	v_cvt_pk_bf16_f32 v106, v154, v155
	s_mov_b64 s[12:13], -1
	s_waitcnt lgkmcnt(0)
	v_add_f32_e32 v96, v96, v115
	s_cbranch_scc0 .LBB0_630
	s_lshl_b32 s12, s93, 8
	s_ashr_i32 s13, s12, 31
	v_lshl_add_u64 v[154:155], s[12:13], 1, v[112:113]
	global_store_dwordx4 v[154:155], v[106:109], off
	s_and_saveexec_b64 s[12:13], s[8:9]
	s_cbranch_execz .LBB0_629
	s_lshl_b32 s22, s93, 3
	s_ashr_i32 s23, s22, 31
	v_lshl_add_u64 v[154:155], s[22:23], 2, v[110:111]
	global_store_dword v[154:155], v96, off

.LBB0_661:
	s_andn2_b64 vcc, exec, s[14:15]
	s_cbranch_vccnz .LBB0_670
	v_pk_mul_f32 v[98:99], v[106:107], v[106:107]
	v_pk_mul_f32 v[100:101], v[108:109], v[108:109]
	v_add_f32_e32 v96, v98, v99
	v_add_f32_e32 v96, v100, v96
	v_pk_mul_f32 v[102:103], v[154:155], v[154:155]
	v_add_f32_e32 v96, v101, v96
	v_add_f32_e32 v96, v102, v96
	v_pk_mul_f32 v[104:105], v[156:157], v[156:157]
	v_add_f32_e32 v96, v103, v96
	v_add_f32_e32 v96, v104, v96
	v_add_f32_e32 v96, v105, v96
	v_mov_b32_e32 v98, v96
	s_nop 1
	v_permlane16_swap_b32_e32 v98, v96
	s_cmp_lt_i32 s95, 3
	v_cvt_pk_bf16_f32 v99, v108, v109
	v_cvt_pk_bf16_f32 v100, v154, v155
	v_cvt_pk_bf16_f32 v101, v156, v157
	s_waitcnt lgkmcnt(0)
	v_add_f32_e32 v96, v96, v98
	v_mov_b32_e32 v102, v96
	s_nop 1
	v_permlane32_swap_b32_e32 v102, v96
	v_cvt_pk_bf16_f32 v98, v106, v107
	s_mov_b64 s[14:15], -1
	s_waitcnt lgkmcnt(0)
	v_add_f32_e32 v96, v96, v102
	s_cbranch_scc1 .LBB0_666
	s_add_i32 s1, s94, -2
	s_lshl_b32 s48, s1, 8
	v_lshl_add_u64 v[102:103], v[152:153], 0, s[48:49]
	global_store_dwordx4 v[102:103], v[98:101], off
	s_and_saveexec_b64 s[14:15], s[8:9]
	s_cbranch_execz .LBB0_665
	s_lshl_b32 s48, s1, 2
	v_lshl_add_u64 v[102:103], s[48:49], 2, v[150:151]
	global_store_dword v[102:103], v96, off

.LBB0_692:
	s_nop 0
	v_lshlrev_b64 v[88:89], 9, v[98:99]
	v_lshl_add_u64 v[108:109], v[126:127], 0, v[88:89]
	v_lshlrev_b64 v[88:89], 5, v[98:99]
	v_lshlrev_b64 v[116:117], 6, v[98:99]
	v_lshl_add_u64 v[106:107], s[54:55], 0, v[88:89]
	v_mad_i64_i32 v[94:95], s[22:23], v98, s36, v[128:129]
	s_andn2_b64 vcc, exec, s[14:15]
	v_lshl_add_u64 v[92:93], s[24:25], 0, v[116:117]
	s_cbranch_vccnz .LBB0_701
	v_pk_mul_f32 v[88:89], v[110:111], v[110:111]
	v_pk_mul_f32 v[90:91], v[118:119], v[118:119]
	v_add_f32_e32 v88, v88, v89
	v_add_f32_e32 v88, v90, v88
	v_pk_mul_f32 v[152:153], v[120:121], v[120:121]
	v_add_f32_e32 v88, v91, v88
	v_add_f32_e32 v88, v152, v88
	v_pk_mul_f32 v[154:155], v[150:151], v[150:151]
	v_add_f32_e32 v88, v153, v88
	v_add_f32_e32 v88, v154, v88
	v_add_f32_e32 v88, v155, v88
	v_mov_b32_e32 v89, v88
	s_nop 1
	v_permlane16_swap_b32_e32 v89, v88
	s_cmp_lg_u32 s93, 2
	v_cvt_pk_bf16_f32 v90, v120, v121
	v_cvt_pk_bf16_f32 v91, v150, v151
	s_mov_b64 s[14:15], -1
	s_waitcnt lgkmcnt(0)
	v_add_f32_e32 v96, v88, v89
	v_mov_b32_e32 v99, v96
	s_nop 1
	v_permlane32_swap_b32_e32 v99, v96
	v_cvt_pk_bf16_f32 v88, v110, v111
	v_cvt_pk_bf16_f32 v89, v118, v119
	s_waitcnt lgkmcnt(0)
	v_add_f32_e32 v96, v96, v99
	s_cbranch_scc0 .LBB0_697
	s_lshl_b32 s14, s93, 8
	s_ashr_i32 s15, s14, 31
	v_lshl_add_u64 v[110:111], s[14:15], 1, v[94:95]
	global_store_dwordx4 v[110:111], v[88:91], off
	s_and_saveexec_b64 s[14:15], s[8:9]
	s_cbranch_execz .LBB0_696
	s_lshl_b32 s22, s93, 3
	s_ashr_i32 s23, s22, 31
	v_lshl_add_u64 v[110:111], s[22:23], 2, v[92:93]
	global_store_dword v[110:111], v96, off

.LBB0_1832:
	s_or_b64 exec, exec, s[70:71]
	v_lshlrev_b32_e32 v98, 16, v142
	s_waitcnt lgkmcnt(0)
	v_and_b32_e32 v99, 0xffff0000, v142
	v_pk_add_f32 v[92:93], v[92:93], v[98:99]
	v_lshlrev_b32_e32 v98, 16, v143
	v_and_b32_e32 v99, 0xffff0000, v143
	v_pk_add_f32 v[94:95], v[94:95], v[98:99]
	v_lshlrev_b32_e32 v98, 16, v144
	v_and_b32_e32 v99, 0xffff0000, v144
	v_pk_add_f32 v[98:99], v[88:89], v[98:99]
	v_lshlrev_b32_e32 v88, 16, v145
	v_and_b32_e32 v89, 0xffff0000, v145
	v_pk_add_f32 v[100:101], v[90:91], v[88:89]
	v_cvt_pk_bf16_f32 v88, v92, v93
	v_and_b32_e32 v93, 0xffff0000, v88
	v_cvt_pk_bf16_f32 v89, v94, v95
	v_lshlrev_b32_e32 v92, 16, v88
	v_mul_f32_e32 v102, v93, v93
	v_lshlrev_b32_e32 v94, 16, v89
	v_fmac_f32_e32 v102, v92, v92
	v_cvt_pk_bf16_f32 v90, v98, v99
	v_and_b32_e32 v95, 0xffff0000, v89
	v_fmac_f32_e32 v102, v94, v94
	v_lshlrev_b32_e32 v92, 16, v138
	v_and_b32_e32 v93, 0xffff0000, v138
	v_lshlrev_b32_e32 v98, 16, v90
	v_fmac_f32_e32 v102, v95, v95
	v_pk_add_f32 v[84:85], v[84:85], v[92:93]
	v_lshlrev_b32_e32 v92, 16, v139
	v_and_b32_e32 v93, 0xffff0000, v139
	v_cvt_pk_bf16_f32 v91, v100, v101
	v_and_b32_e32 v99, 0xffff0000, v90
	v_fmac_f32_e32 v102, v98, v98
	v_pk_add_f32 v[86:87], v[86:87], v[92:93]
	v_lshlrev_b32_e32 v92, 16, v140
	v_and_b32_e32 v93, 0xffff0000, v140
	v_lshlrev_b32_e32 v100, 16, v91
	v_fmac_f32_e32 v102, v99, v99
	v_pk_add_f32 v[80:81], v[80:81], v[92:93]
	v_lshlrev_b32_e32 v92, 16, v141
	v_and_b32_e32 v93, 0xffff0000, v141
	v_and_b32_e32 v101, 0xffff0000, v91
	v_fmac_f32_e32 v102, v100, v100
	v_pk_add_f32 v[92:93], v[82:83], v[92:93]
	v_cvt_pk_bf16_f32 v82, v84, v85
	v_fmac_f32_e32 v102, v101, v101
	v_cvt_pk_bf16_f32 v84, v80, v81
	v_lshlrev_b32_e32 v80, 16, v82
	v_cvt_pk_bf16_f32 v83, v86, v87
	v_and_b32_e32 v81, 0xffff0000, v82
	v_fmac_f32_e32 v102, v80, v80
	v_lshlrev_b32_e32 v86, 16, v83
	v_fmac_f32_e32 v102, v81, v81
	v_and_b32_e32 v87, 0xffff0000, v83
	v_fmac_f32_e32 v102, v86, v86
	v_cvt_pk_bf16_f32 v85, v92, v93
	v_lshlrev_b32_e32 v92, 16, v84
	v_fmac_f32_e32 v102, v87, v87
	v_and_b32_e32 v93, 0xffff0000, v84
	v_fmac_f32_e32 v102, v92, v92
	v_lshlrev_b32_e32 v94, 16, v85
	v_fmac_f32_e32 v102, v93, v93
	v_and_b32_e32 v95, 0xffff0000, v85
	v_fmac_f32_e32 v102, v94, v94
	v_fmac_f32_e32 v102, v95, v95
	v_mov_b32_e32 v80, v102
	s_nop 1
	v_permlane16_swap_b32_e32 v80, v102
	v_lshl_add_u64 v[86:87], s[50:51], 0, v[180:181]
	v_lshl_add_u64 v[86:87], v[168:169], 1, v[86:87]
	global_store_dwordx4 v[86:87], v[88:91], off
	global_store_dwordx4 v[86:87], v[82:85], off offset:256
	s_waitcnt lgkmcnt(0)
	v_add_f32_e32 v80, v102, v80
	ds_bpermute_b32 v81, v191, v80
	s_and_saveexec_b64 s[70:71], vcc
	s_cbranch_execz .LBB0_1834
	s_waitcnt lgkmcnt(0)
	v_add_f32_e32 v82, v80, v81
	s_lshl_b32 s22, s44, 2
	v_lshlrev_b64 v[80:81], 6, v[178:179]
	s_ashr_i32 s23, s22, 31
	v_lshl_add_u64 v[80:81], s[52:53], 0, v[80:81]
	v_lshl_add_u64 v[80:81], s[22:23], 2, v[80:81]
	s_lshl_b32 s48, s78, 2
	v_lshl_add_u64 v[80:81], v[80:81], 0, s[48:49]
	global_store_dword v[80:81], v82, off
.LBB0_1834:
	s_or_b64 exec, exec, s[70:71]
	v_lshlrev_b32_e32 v80, 16, v134
	s_waitcnt lgkmcnt(0)
	v_and_b32_e32 v81, 0xffff0000, v134
	v_pk_add_f32 v[76:77], v[76:77], v[80:81]
	v_lshlrev_b32_e32 v80, 16, v135
	v_and_b32_e32 v81, 0xffff0000, v135
	v_pk_add_f32 v[78:79], v[78:79], v[80:81]
	v_lshlrev_b32_e32 v80, 16, v136
	v_and_b32_e32 v81, 0xffff0000, v136
	v_pk_add_f32 v[80:81], v[72:73], v[80:81]
	v_lshlrev_b32_e32 v72, 16, v137
	v_and_b32_e32 v73, 0xffff0000, v137
	v_pk_add_f32 v[82:83], v[74:75], v[72:73]
	v_cvt_pk_bf16_f32 v72, v76, v77
	v_and_b32_e32 v77, 0xffff0000, v72
	v_cvt_pk_bf16_f32 v73, v78, v79
	v_lshlrev_b32_e32 v76, 16, v72
	v_mul_f32_e32 v84, v77, v77
	v_lshlrev_b32_e32 v78, 16, v73
	v_fmac_f32_e32 v84, v76, v76
	v_cvt_pk_bf16_f32 v74, v80, v81
	v_and_b32_e32 v79, 0xffff0000, v73
	v_fmac_f32_e32 v84, v78, v78
	v_lshlrev_b32_e32 v76, 16, v130
	v_and_b32_e32 v77, 0xffff0000, v130
	v_lshlrev_b32_e32 v80, 16, v74
	v_fmac_f32_e32 v84, v79, v79
	v_pk_add_f32 v[68:69], v[68:69], v[76:77]
	v_lshlrev_b32_e32 v76, 16, v131
	v_and_b32_e32 v77, 0xffff0000, v131
	v_cvt_pk_bf16_f32 v75, v82, v83
	v_and_b32_e32 v81, 0xffff0000, v74
	v_fmac_f32_e32 v84, v80, v80
	v_pk_add_f32 v[70:71], v[70:71], v[76:77]
	v_lshlrev_b32_e32 v76, 16, v132
	v_and_b32_e32 v77, 0xffff0000, v132
	v_lshlrev_b32_e32 v82, 16, v75
	v_fmac_f32_e32 v84, v81, v81
	v_pk_add_f32 v[64:65], v[64:65], v[76:77]
	v_lshlrev_b32_e32 v76, 16, v133
	v_and_b32_e32 v77, 0xffff0000, v133
	v_and_b32_e32 v83, 0xffff0000, v75
	v_fmac_f32_e32 v84, v82, v82
	v_pk_add_f32 v[76:77], v[66:67], v[76:77]
	v_cvt_pk_bf16_f32 v66, v68, v69
	v_fmac_f32_e32 v84, v83, v83
	v_cvt_pk_bf16_f32 v68, v64, v65
	v_lshlrev_b32_e32 v64, 16, v66
	v_cvt_pk_bf16_f32 v67, v70, v71
	v_and_b32_e32 v65, 0xffff0000, v66
	v_fmac_f32_e32 v84, v64, v64
	v_lshlrev_b32_e32 v70, 16, v67
	v_fmac_f32_e32 v84, v65, v65
	v_and_b32_e32 v71, 0xffff0000, v67
	v_fmac_f32_e32 v84, v70, v70
	v_cvt_pk_bf16_f32 v69, v76, v77
	v_lshlrev_b32_e32 v76, 16, v68
	v_fmac_f32_e32 v84, v71, v71
	v_and_b32_e32 v77, 0xffff0000, v68
	v_fmac_f32_e32 v84, v76, v76
	v_lshlrev_b32_e32 v78, 16, v69
	v_fmac_f32_e32 v84, v77, v77
	v_and_b32_e32 v79, 0xffff0000, v69
	v_fmac_f32_e32 v84, v78, v78
	v_fmac_f32_e32 v84, v79, v79
	v_mov_b32_e32 v64, v84
	s_nop 1
	v_permlane16_swap_b32_e32 v64, v84
	v_lshl_add_u64 v[70:71], s[50:51], 0, v[176:177]
	v_lshl_add_u64 v[70:71], v[168:169], 1, v[70:71]
	global_store_dwordx4 v[70:71], v[72:75], off
	global_store_dwordx4 v[70:71], v[66:69], off offset:256
	s_waitcnt lgkmcnt(0)
	v_add_f32_e32 v64, v84, v64
	ds_bpermute_b32 v65, v191, v64
	s_and_saveexec_b64 s[70:71], vcc
	s_cbranch_execz .LBB0_1836
	s_waitcnt lgkmcnt(0)
	v_add_f32_e32 v66, v64, v65
	s_lshl_b32 s22, s44, 2
	v_lshlrev_b64 v[64:65], 6, v[174:175]
	s_ashr_i32 s23, s22, 31
	v_lshl_add_u64 v[64:65], s[52:53], 0, v[64:65]
	v_lshl_add_u64 v[64:65], s[22:23], 2, v[64:65]
	s_lshl_b32 s48, s78, 2
	v_lshl_add_u64 v[64:65], v[64:65], 0, s[48:49]
	global_store_dword v[64:65], v66, off

.LBB0_1930:
	v_mov_b32_e32 v180, v147
	v_mov_b32_e32 v142, v149
	s_add_i32 s22, 0, 0x21000
	v_add_u32_e32 v181, s86, v142
	v_lshlrev_b32_e32 v142, 4, v180
	v_lshlrev_b32_e32 v143, 6, v181
	s_waitcnt vmcnt(16)
	s_barrier
	v_add3_u32 v146, s22, v142, v143
	ds_read_b128 v[142:145], v146
	ds_read_b128 v[154:157], v146 offset:1024
	ds_read_b128 v[158:161], v146 offset:2048
	ds_read_b128 v[162:165], v146 offset:3072
	v_and_b32_e32 v150, 64, v225
	v_xor_b32_e32 v148, 16, v225
	v_add_u32_e32 v150, 64, v150
	v_cmp_lt_i32_e32 vcc, v148, v150
	s_waitcnt lgkmcnt(0)
	v_mov_b32_e32 v166, v143
	v_mov_b32_e32 v167, v144
	v_mov_b32_e32 v143, v145
	v_cndmask_b32_e32 v148, v225, v148, vcc
	v_pk_add_f32 v[142:143], v[166:167], v[142:143]
	v_lshlrev_b32_e32 v182, 2, v148
	v_add_f32_e32 v142, v142, v143
	v_mov_b32_e32 v143, v142
	s_nop 1
	v_permlane16_swap_b32_e32 v143, v142
	v_xor_b32_e32 v144, 32, v225
	v_cmp_lt_i32_e32 vcc, v144, v150
	v_mov_b32_e32 v178, v155
	v_mov_b32_e32 v179, v156
	v_cndmask_b32_e32 v144, v225, v144, vcc
	v_lshlrev_b32_e32 v183, 2, v144
	s_waitcnt lgkmcnt(0)
	v_add_f32_e32 v148, v142, v143
	v_mov_b32_e32 v150, v148
	s_nop 1
	v_permlane32_swap_b32_e32 v150, v148
	v_mov_b32_e32 v155, v157
	v_pk_add_f32 v[154:155], v[178:179], v[154:155]
	ds_read_b128 v[142:145], v146 offset:8192
	ds_read_b128 v[166:169], v146 offset:9216
	ds_read_b128 v[170:173], v146 offset:10240
	ds_read_b128 v[174:177], v146 offset:11264
	s_and_b64 vcc, exec, s[6:7]
	s_waitcnt lgkmcnt(0)
	v_add_f32_e32 v146, v148, v150
	v_add_f32_e32 v148, v154, v155
	v_mov_b32_e32 v154, v159
	v_mov_b32_e32 v155, v160
	v_mov_b32_e32 v159, v161
	v_pk_add_f32 v[154:155], v[154:155], v[158:159]
	v_mov_b32_e32 v150, v148
	s_nop 1
	v_permlane16_swap_b32_e32 v150, v148
	v_add_f32_e32 v152, v154, v155
	v_mov_b32_e32 v154, v152
	s_nop 1
	v_permlane16_swap_b32_e32 v154, v152
	v_fmamk_f32 v146, v146, 0x3a800000, v226
	v_rsq_f32_e32 v156, v146
	s_waitcnt lgkmcnt(0)
	v_add_f32_e32 v146, v148, v150
	v_mov_b32_e32 v155, v164
	v_add_f32_e32 v150, v152, v154
	v_mov_b32_e32 v154, v163
	v_mov_b32_e32 v163, v165
	v_pk_add_f32 v[154:155], v[154:155], v[162:163]
	v_mov_b32_e32 v148, v146
	s_nop 1
	v_permlane32_swap_b32_e32 v148, v146
	v_add_f32_e32 v155, v154, v155
	v_mov_b32_e32 v158, v143
	v_mov_b32_e32 v159, v144
	v_mov_b32_e32 v143, v145
	v_mov_b32_e32 v157, v155
	s_nop 1
	v_permlane16_swap_b32_e32 v157, v155
	v_pk_add_f32 v[142:143], v[158:159], v[142:143]
	v_mov_b32_e32 v152, v150
	s_nop 1
	v_permlane32_swap_b32_e32 v152, v150
	v_add_f32_e32 v142, v142, v143
	v_mov_b32_e32 v143, v142
	s_nop 1
	v_permlane16_swap_b32_e32 v143, v142
	s_waitcnt lgkmcnt(0)
	v_add_f32_e32 v146, v146, v148
	v_fmamk_f32 v146, v146, 0x3a800000, v226
	v_add_f32_e32 v148, v155, v157
	v_rsq_f32_e32 v154, v146
	v_add_f32_e32 v146, v150, v152
	v_mov_b32_e32 v150, v148
	s_nop 1
	v_permlane32_swap_b32_e32 v150, v148
	v_add_f32_e32 v145, v142, v143
	v_mov_b32_e32 v142, v167
	v_mov_b32_e32 v143, v168
	v_mov_b32_e32 v167, v169
	v_fmamk_f32 v144, v146, 0x3a800000, v226
	v_mov_b32_e32 v146, v145
	s_nop 1
	v_permlane32_swap_b32_e32 v146, v145
	v_pk_add_f32 v[142:143], v[142:143], v[166:167]
	v_rsq_f32_e32 v152, v144
	v_add_f32_e32 v142, v142, v143
	v_mov_b32_e32 v143, v142
	s_nop 1
	v_permlane16_swap_b32_e32 v143, v142
	s_waitcnt lgkmcnt(0)
	v_add_f32_e32 v144, v148, v150
	v_fmamk_f32 v144, v144, 0x3a800000, v226
	v_rsq_f32_e32 v150, v144
	v_add_f32_e32 v144, v145, v146
	v_fmamk_f32 v144, v144, 0x3a800000, v226
	v_rsq_f32_e32 v148, v144
	v_add_f32_e32 v144, v142, v143
	v_mov_b32_e32 v142, v171
	v_mov_b32_e32 v143, v172
	v_mov_b32_e32 v171, v173
	v_pk_add_f32 v[142:143], v[142:143], v[170:171]
	v_pk_mul_f32 v[158:159], v[126:127], v[156:157] op_sel_hi:[1,0]
	v_add_f32_e32 v146, v142, v143
	v_mov_b32_e32 v142, v175
	v_mov_b32_e32 v143, v176
	v_mov_b32_e32 v175, v177
	v_pk_add_f32 v[142:143], v[142:143], v[174:175]
	v_mul_f32_e32 v126, 0xbfb8aa3b, v158
	v_add_f32_e32 v142, v142, v143
	v_mov_b32_e32 v143, v142
	s_nop 1
	v_permlane16_swap_b32_e32 v143, v142
	v_exp_f32_e32 v127, v126
	v_pk_mul_f32 v[128:129], v[128:129], v[156:157] op_sel_hi:[1,0]
	v_pk_mul_f32 v[122:123], v[122:123], v[156:157] op_sel_hi:[1,0]
	v_pk_mul_f32 v[118:119], v[118:119], v[156:157] op_sel_hi:[1,0]
	s_waitcnt lgkmcnt(0)
	v_add_f32_e32 v142, v142, v143
	v_mov_b32_e32 v143, v142
	s_nop 1
	v_permlane32_swap_b32_e32 v143, v142
	v_add_f32_e32 v127, 1.0, v127
	v_rcp_f32_e32 v162, v127
	v_pk_mul_f32 v[122:123], v[158:159], v[122:123]
	v_pk_mul_f32 v[124:125], v[124:125], v[156:157] op_sel_hi:[1,0]
	s_waitcnt lgkmcnt(0)
	v_add_f32_e32 v142, v142, v143
	v_mul_f32_e32 v143, 0xbfb8aa3b, v159
	v_exp_f32_e32 v143, v143
	v_pk_mul_f32 v[114:115], v[114:115], v[156:157] op_sel_hi:[1,0]
	v_pk_mul_f32 v[124:125], v[128:129], v[124:125]
	v_pk_mul_f32 v[114:115], v[118:119], v[114:115]
	v_add_f32_e32 v127, 1.0, v143
	v_rcp_f32_e32 v163, v127
	v_mul_f32_e32 v127, 0xbfb8aa3b, v128
	v_exp_f32_e32 v127, v127
	v_mul_f32_e32 v143, 0xbfb8aa3b, v129
	v_exp_f32_e32 v143, v143
	v_mul_f32_e32 v128, 0xbfb8aa3b, v119
	v_add_f32_e32 v127, 1.0, v127
	v_rcp_f32_e32 v158, v127
	v_add_f32_e32 v127, 1.0, v143
	v_rcp_f32_e32 v159, v127
	v_mul_f32_e32 v127, 0xbfb8aa3b, v118
	v_exp_f32_e32 v127, v127
	v_pk_mul_f32 v[118:119], v[120:121], v[156:157] op_sel_hi:[1,0]
	v_exp_f32_e32 v129, v128
	v_mul_f32_e32 v120, 0xbfb8aa3b, v118
	v_mul_f32_e32 v121, 0xbfb8aa3b, v119
	v_exp_f32_e32 v120, v120
	v_exp_f32_e32 v121, v121
	v_mov_b32_e32 v145, v144
	s_nop 1
	v_permlane32_swap_b32_e32 v145, v144
	v_mov_b32_e32 v155, v146
	s_nop 1
	v_permlane16_swap_b32_e32 v155, v146
	v_add_f32_e32 v127, 1.0, v127
	v_rcp_f32_e32 v128, v127
	v_add_f32_e32 v127, 1.0, v129
	v_rcp_f32_e32 v129, v127
	v_add_f32_e32 v120, 1.0, v120
	v_add_f32_e32 v121, 1.0, v121
	v_rcp_f32_e32 v120, v120
	v_rcp_f32_e32 v121, v121
	s_waitcnt lgkmcnt(0)
	v_add_f32_e32 v144, v144, v145
	v_add_f32_e32 v145, v146, v155
	v_pk_mul_f32 v[116:117], v[116:117], v[156:157] op_sel_hi:[1,0]
	ds_bpermute_b32 v155, v183, v145
	v_pk_mul_f32 v[114:115], v[114:115], v[128:129]
	v_pk_mul_f32 v[116:117], v[118:119], v[116:117]
	v_lshl_add_u32 v126, s68, 8, v181
	v_pk_mul_f32 v[120:121], v[116:117], v[120:121]
	v_cvt_pk_bf16_f32 v118, v114, v115
	v_mov_b64_e32 v[114:115], s[50:51]
	v_cvt_pk_bf16_f32 v119, v120, v121
	v_mad_i64_i32 v[120:121], s[22:23], v126, s65, v[114:115]
	s_lshl_b32 s22, s93, 7
	v_pk_mul_f32 v[122:123], v[122:123], v[162:163]
	s_ashr_i32 s23, s22, 31
	v_lshlrev_b32_e32 v160, 3, v180
	v_cvt_pk_bf16_f32 v116, v122, v123
	s_lshl_b64 s[68:69], s[22:23], 1
	s_waitcnt lgkmcnt(0)
	v_pk_mul_f32 v[122:123], v[110:111], v[154:155] op_sel_hi:[1,0]
	v_ashrrev_i32_e32 v161, 31, v160
	v_pk_mul_f32 v[124:125], v[124:125], v[158:159]
	v_lshl_add_u64 v[120:121], v[120:121], 0, s[68:69]
	v_mul_f32_e32 v110, 0xbfb8aa3b, v122
	v_cvt_pk_bf16_f32 v117, v124, v125
	v_lshl_add_u64 v[120:121], v[120:121], 0, s[48:49]
	v_exp_f32_e32 v124, v110
	v_lshlrev_b64 v[110:111], 1, v[160:161]
	v_lshl_add_u64 v[120:121], v[120:121], 0, v[110:111]
	global_store_dwordx4 v[120:121], v[116:119], off
	v_pk_mul_f32 v[112:113], v[112:113], v[154:155] op_sel_hi:[1,0]
	v_pk_mul_f32 v[106:107], v[106:107], v[154:155] op_sel_hi:[1,0]
	v_mul_f32_e32 v117, 0xbfb8aa3b, v123
	v_exp_f32_e32 v117, v117
	v_add_f32_e32 v116, 1.0, v124
	v_mul_f32_e32 v118, 0xbfb8aa3b, v112
	v_rcp_f32_e32 v116, v116
	v_add_f32_e32 v117, 1.0, v117
	v_rcp_f32_e32 v117, v117
	v_exp_f32_e32 v118, v118
	v_pk_mul_f32 v[106:107], v[122:123], v[106:107]
	v_pk_mul_f32 v[102:103], v[102:103], v[154:155] op_sel_hi:[1,0]
	v_pk_mul_f32 v[108:109], v[108:109], v[154:155] op_sel_hi:[1,0]
	v_mul_f32_e32 v119, 0xbfb8aa3b, v113
	v_pk_mul_f32 v[106:107], v[106:107], v[116:117]
	v_add_f32_e32 v116, 1.0, v118
	v_mul_f32_e32 v118, 0xbfb8aa3b, v102
	v_pk_mul_f32 v[108:109], v[112:113], v[108:109]
	v_mul_f32_e32 v113, 0xbfb8aa3b, v103
	v_pk_mul_f32 v[98:99], v[98:99], v[154:155] op_sel_hi:[1,0]
	v_exp_f32_e32 v118, v118
	v_exp_f32_e32 v113, v113
	v_pk_mul_f32 v[98:99], v[102:103], v[98:99]
	v_pk_mul_f32 v[102:103], v[104:105], v[154:155] op_sel_hi:[1,0]
	v_add_f32_e32 v112, 1.0, v118
	v_mul_f32_e32 v104, 0xbfb8aa3b, v102
	v_mul_f32_e32 v105, 0xbfb8aa3b, v103
	v_exp_f32_e32 v104, v104
	v_exp_f32_e32 v105, v105
	v_add_f32_e32 v113, 1.0, v113
	v_exp_f32_e32 v119, v119
	v_rcp_f32_e32 v112, v112
	v_rcp_f32_e32 v113, v113
	v_add_f32_e32 v104, 1.0, v104
	v_add_f32_e32 v105, 1.0, v105
	v_rcp_f32_e32 v104, v104
	v_rcp_f32_e32 v105, v105
	v_add_f32_e32 v117, 1.0, v119
	v_pk_mul_f32 v[112:113], v[98:99], v[112:113]
	v_pk_mul_f32 v[98:99], v[100:101], v[154:155] op_sel_hi:[1,0]
	v_rcp_f32_e32 v116, v116
	v_rcp_f32_e32 v117, v117
	v_pk_mul_f32 v[98:99], v[102:103], v[98:99]
	v_cvt_pk_bf16_f32 v100, v112, v113
	v_pk_mul_f32 v[102:103], v[98:99], v[104:105]
	v_add_u32_e32 v104, 16, v126
	v_cvt_pk_bf16_f32 v101, v102, v103
	v_mad_i64_i32 v[102:103], s[22:23], v104, s65, v[114:115]
	v_lshl_add_u64 v[102:103], v[102:103], 0, s[68:69]
	v_pk_mul_f32 v[108:109], v[108:109], v[116:117]
	v_lshl_add_u64 v[102:103], v[102:103], 0, s[48:49]
	v_cvt_pk_bf16_f32 v98, v106, v107
	v_cvt_pk_bf16_f32 v99, v108, v109
	v_pk_mul_f32 v[92:93], v[92:93], v[152:153] op_sel_hi:[1,0]
	v_lshl_add_u64 v[102:103], v[102:103], 0, v[110:111]
	v_mul_f32_e32 v104, 0xbfb8aa3b, v92
	global_store_dwordx4 v[102:103], v[98:101], off
	v_exp_f32_e32 v104, v104
	v_pk_mul_f32 v[88:89], v[88:89], v[152:153] op_sel_hi:[1,0]
	v_mul_f32_e32 v99, 0xbfb8aa3b, v93
	v_exp_f32_e32 v99, v99
	v_add_f32_e32 v98, 1.0, v104
	v_pk_mul_f32 v[88:89], v[92:93], v[88:89]
	v_rcp_f32_e32 v98, v98
	v_add_f32_e32 v92, 1.0, v99
	v_rcp_f32_e32 v99, v92
	v_pk_mul_f32 v[92:93], v[94:95], v[152:153] op_sel_hi:[1,0]
	v_pk_mul_f32 v[84:85], v[84:85], v[152:153] op_sel_hi:[1,0]
	v_pk_mul_f32 v[90:91], v[90:91], v[152:153] op_sel_hi:[1,0]
	v_mul_f32_e32 v95, 0xbfb8aa3b, v93
	v_pk_mul_f32 v[88:89], v[88:89], v[98:99]
	v_mul_f32_e32 v98, 0xbfb8aa3b, v84
	v_pk_mul_f32 v[90:91], v[92:93], v[90:91]
	v_mul_f32_e32 v93, 0xbfb8aa3b, v85
	v_pk_mul_f32 v[80:81], v[80:81], v[152:153] op_sel_hi:[1,0]
	v_exp_f32_e32 v98, v98
	v_exp_f32_e32 v93, v93
	v_pk_mul_f32 v[80:81], v[84:85], v[80:81]
	v_pk_mul_f32 v[84:85], v[86:87], v[152:153] op_sel_hi:[1,0]
	v_mul_f32_e32 v94, 0xbfb8aa3b, v92
	v_mul_f32_e32 v86, 0xbfb8aa3b, v84
	v_mul_f32_e32 v87, 0xbfb8aa3b, v85
	v_exp_f32_e32 v86, v86
	v_exp_f32_e32 v87, v87
	v_add_f32_e32 v92, 1.0, v98
	v_add_f32_e32 v93, 1.0, v93
	v_exp_f32_e32 v94, v94
	v_exp_f32_e32 v95, v95
	v_rcp_f32_e32 v92, v92
	v_rcp_f32_e32 v93, v93
	v_add_f32_e32 v86, 1.0, v86
	v_add_f32_e32 v87, 1.0, v87
	v_rcp_f32_e32 v86, v86
	v_rcp_f32_e32 v87, v87
	v_add_f32_e32 v94, 1.0, v94
	v_add_f32_e32 v95, 1.0, v95
	v_pk_mul_f32 v[92:93], v[80:81], v[92:93]
	v_pk_mul_f32 v[80:81], v[82:83], v[152:153] op_sel_hi:[1,0]
	v_rcp_f32_e32 v94, v94
	v_rcp_f32_e32 v95, v95
	v_pk_mul_f32 v[80:81], v[84:85], v[80:81]
	v_cvt_pk_bf16_f32 v82, v92, v93
	v_pk_mul_f32 v[84:85], v[80:81], v[86:87]
	v_add_u32_e32 v86, 32, v126
	v_cvt_pk_bf16_f32 v83, v84, v85
	v_mad_i64_i32 v[84:85], s[22:23], v86, s65, v[114:115]
	v_lshl_add_u64 v[84:85], v[84:85], 0, s[68:69]
	v_pk_mul_f32 v[90:91], v[90:91], v[94:95]
	v_lshl_add_u64 v[84:85], v[84:85], 0, s[48:49]
	v_cvt_pk_bf16_f32 v80, v88, v89
	v_cvt_pk_bf16_f32 v81, v90, v91
	v_pk_mul_f32 v[76:77], v[76:77], v[150:151] op_sel_hi:[1,0]
	v_lshl_add_u64 v[84:85], v[84:85], 0, v[110:111]
	v_mul_f32_e32 v86, 0xbfb8aa3b, v76
	global_store_dwordx4 v[84:85], v[80:83], off
	v_exp_f32_e32 v86, v86
	v_pk_mul_f32 v[72:73], v[72:73], v[150:151] op_sel_hi:[1,0]
	v_mul_f32_e32 v81, 0xbfb8aa3b, v77
	v_exp_f32_e32 v81, v81
	v_add_f32_e32 v80, 1.0, v86
	v_pk_mul_f32 v[72:73], v[76:77], v[72:73]
	v_rcp_f32_e32 v80, v80
	v_add_f32_e32 v76, 1.0, v81
	v_rcp_f32_e32 v81, v76
	v_pk_mul_f32 v[76:77], v[78:79], v[150:151] op_sel_hi:[1,0]
	v_pk_mul_f32 v[68:69], v[68:69], v[150:151] op_sel_hi:[1,0]
	v_pk_mul_f32 v[74:75], v[74:75], v[150:151] op_sel_hi:[1,0]
	v_mul_f32_e32 v79, 0xbfb8aa3b, v77
	v_pk_mul_f32 v[72:73], v[72:73], v[80:81]
	v_mul_f32_e32 v80, 0xbfb8aa3b, v68
	v_pk_mul_f32 v[74:75], v[76:77], v[74:75]
	v_mul_f32_e32 v77, 0xbfb8aa3b, v69
	v_pk_mul_f32 v[64:65], v[64:65], v[150:151] op_sel_hi:[1,0]
	v_exp_f32_e32 v80, v80
	v_exp_f32_e32 v77, v77
	v_pk_mul_f32 v[64:65], v[68:69], v[64:65]
	v_pk_mul_f32 v[68:69], v[70:71], v[150:151] op_sel_hi:[1,0]
	v_mul_f32_e32 v78, 0xbfb8aa3b, v76
	v_mul_f32_e32 v70, 0xbfb8aa3b, v68
	v_mul_f32_e32 v71, 0xbfb8aa3b, v69
	v_exp_f32_e32 v70, v70
	v_exp_f32_e32 v71, v71
	v_add_f32_e32 v76, 1.0, v80
	v_add_f32_e32 v77, 1.0, v77
	v_exp_f32_e32 v78, v78
	v_exp_f32_e32 v79, v79
	v_rcp_f32_e32 v76, v76
	v_rcp_f32_e32 v77, v77
	v_add_f32_e32 v70, 1.0, v70
	v_add_f32_e32 v71, 1.0, v71
	v_rcp_f32_e32 v70, v70
	v_rcp_f32_e32 v71, v71
	v_add_f32_e32 v78, 1.0, v78
	v_add_f32_e32 v79, 1.0, v79
	v_pk_mul_f32 v[76:77], v[64:65], v[76:77]
	v_pk_mul_f32 v[64:65], v[66:67], v[150:151] op_sel_hi:[1,0]
	v_rcp_f32_e32 v78, v78
	v_rcp_f32_e32 v79, v79
	v_pk_mul_f32 v[64:65], v[68:69], v[64:65]
	v_cvt_pk_bf16_f32 v66, v76, v77
	v_pk_mul_f32 v[68:69], v[64:65], v[70:71]
	v_add_u32_e32 v70, 48, v126
	v_cvt_pk_bf16_f32 v67, v68, v69
	v_mad_i64_i32 v[68:69], s[22:23], v70, s65, v[114:115]
	v_lshl_add_u64 v[68:69], v[68:69], 0, s[68:69]
	v_pk_mul_f32 v[74:75], v[74:75], v[78:79]
	v_lshl_add_u64 v[68:69], v[68:69], 0, s[48:49]
	v_cvt_pk_bf16_f32 v64, v72, v73
	v_cvt_pk_bf16_f32 v65, v74, v75
	v_pk_mul_f32 v[60:61], v[60:61], v[148:149] op_sel_hi:[1,0]
	v_lshl_add_u64 v[68:69], v[68:69], 0, v[110:111]
	v_mul_f32_e32 v70, 0xbfb8aa3b, v60
	global_store_dwordx4 v[68:69], v[64:67], off
	v_exp_f32_e32 v70, v70
	v_pk_mul_f32 v[56:57], v[56:57], v[148:149] op_sel_hi:[1,0]
	v_mul_f32_e32 v65, 0xbfb8aa3b, v61
	v_exp_f32_e32 v65, v65
	v_add_f32_e32 v64, 1.0, v70
	v_pk_mul_f32 v[56:57], v[60:61], v[56:57]
	v_rcp_f32_e32 v64, v64
	v_add_f32_e32 v60, 1.0, v65
	v_rcp_f32_e32 v65, v60
	v_pk_mul_f32 v[60:61], v[62:63], v[148:149] op_sel_hi:[1,0]
	v_pk_mul_f32 v[52:53], v[52:53], v[148:149] op_sel_hi:[1,0]
	v_pk_mul_f32 v[58:59], v[58:59], v[148:149] op_sel_hi:[1,0]
	v_mul_f32_e32 v63, 0xbfb8aa3b, v61
	v_pk_mul_f32 v[56:57], v[56:57], v[64:65]
	v_mul_f32_e32 v64, 0xbfb8aa3b, v52
	v_pk_mul_f32 v[58:59], v[60:61], v[58:59]
	v_mul_f32_e32 v61, 0xbfb8aa3b, v53
	v_pk_mul_f32 v[48:49], v[48:49], v[148:149] op_sel_hi:[1,0]
	v_exp_f32_e32 v64, v64
	v_exp_f32_e32 v61, v61
	v_pk_mul_f32 v[48:49], v[52:53], v[48:49]
	v_pk_mul_f32 v[52:53], v[54:55], v[148:149] op_sel_hi:[1,0]
	v_mul_f32_e32 v62, 0xbfb8aa3b, v60
	v_mul_f32_e32 v54, 0xbfb8aa3b, v52
	v_mul_f32_e32 v55, 0xbfb8aa3b, v53
	v_exp_f32_e32 v54, v54
	v_exp_f32_e32 v55, v55
	v_add_f32_e32 v60, 1.0, v64
	v_add_f32_e32 v61, 1.0, v61
	v_exp_f32_e32 v62, v62
	v_exp_f32_e32 v63, v63
	v_rcp_f32_e32 v60, v60
	v_rcp_f32_e32 v61, v61
	v_add_f32_e32 v54, 1.0, v54
	v_add_f32_e32 v55, 1.0, v55
	v_rcp_f32_e32 v54, v54
	v_rcp_f32_e32 v55, v55
	v_add_f32_e32 v62, 1.0, v62
	v_add_f32_e32 v63, 1.0, v63
	v_pk_mul_f32 v[60:61], v[48:49], v[60:61]
	v_pk_mul_f32 v[48:49], v[50:51], v[148:149] op_sel_hi:[1,0]
	v_fmamk_f32 v144, v144, 0x3a800000, v226
	v_rcp_f32_e32 v62, v62
	v_rcp_f32_e32 v63, v63
	v_pk_mul_f32 v[48:49], v[52:53], v[48:49]
	v_rsq_f32_e32 v146, v144
	v_add_u32_e32 v66, 0x80, v126
	v_pk_mul_f32 v[52:53], v[48:49], v[54:55]
	v_pk_mul_f32 v[58:59], v[58:59], v[62:63]
	v_cvt_pk_bf16_f32 v51, v52, v53
	v_mad_i64_i32 v[52:53], s[22:23], v66, s65, v[114:115]
	v_lshl_add_u64 v[52:53], v[52:53], 0, s[68:69]
	v_lshl_add_u64 v[52:53], v[52:53], 0, s[48:49]
	v_cvt_pk_bf16_f32 v48, v56, v57
	v_cvt_pk_bf16_f32 v49, v58, v59
	v_cvt_pk_bf16_f32 v50, v60, v61
	v_pk_mul_f32 v[44:45], v[44:45], v[146:147] op_sel_hi:[1,0]
	v_lshl_add_u64 v[52:53], v[52:53], 0, v[110:111]
	v_mul_f32_e32 v54, 0xbfb8aa3b, v44
	global_store_dwordx4 v[52:53], v[48:51], off
	v_exp_f32_e32 v54, v54
	v_pk_mul_f32 v[40:41], v[40:41], v[146:147] op_sel_hi:[1,0]
	v_mul_f32_e32 v49, 0xbfb8aa3b, v45
	v_exp_f32_e32 v49, v49
	v_add_f32_e32 v48, 1.0, v54
	v_pk_mul_f32 v[40:41], v[44:45], v[40:41]
	v_rcp_f32_e32 v48, v48
	v_add_f32_e32 v44, 1.0, v49
	v_rcp_f32_e32 v49, v44
	v_pk_mul_f32 v[44:45], v[46:47], v[146:147] op_sel_hi:[1,0]
	v_pk_mul_f32 v[36:37], v[36:37], v[146:147] op_sel_hi:[1,0]
	v_pk_mul_f32 v[42:43], v[42:43], v[146:147] op_sel_hi:[1,0]
	v_mul_f32_e32 v47, 0xbfb8aa3b, v45
	v_pk_mul_f32 v[40:41], v[40:41], v[48:49]
	v_mul_f32_e32 v48, 0xbfb8aa3b, v36
	v_pk_mul_f32 v[42:43], v[44:45], v[42:43]
	v_mul_f32_e32 v45, 0xbfb8aa3b, v37
	v_pk_mul_f32 v[32:33], v[32:33], v[146:147] op_sel_hi:[1,0]
	v_exp_f32_e32 v48, v48
	v_exp_f32_e32 v45, v45
	v_pk_mul_f32 v[32:33], v[36:37], v[32:33]
	v_pk_mul_f32 v[36:37], v[38:39], v[146:147] op_sel_hi:[1,0]
	v_mul_f32_e32 v46, 0xbfb8aa3b, v44
	v_mul_f32_e32 v38, 0xbfb8aa3b, v36
	v_mul_f32_e32 v39, 0xbfb8aa3b, v37
	v_exp_f32_e32 v38, v38
	v_exp_f32_e32 v39, v39
	v_add_f32_e32 v44, 1.0, v48
	v_add_f32_e32 v45, 1.0, v45
	v_exp_f32_e32 v46, v46
	v_exp_f32_e32 v47, v47
	v_rcp_f32_e32 v44, v44
	v_rcp_f32_e32 v45, v45
	v_add_f32_e32 v38, 1.0, v38
	v_add_f32_e32 v39, 1.0, v39
	v_rcp_f32_e32 v38, v38
	v_rcp_f32_e32 v39, v39
	v_add_f32_e32 v144, v145, v155
	v_add_f32_e32 v46, 1.0, v46
	v_add_f32_e32 v47, 1.0, v47
	v_pk_mul_f32 v[44:45], v[32:33], v[44:45]
	v_pk_mul_f32 v[32:33], v[34:35], v[146:147] op_sel_hi:[1,0]
	v_fmamk_f32 v144, v144, 0x3a800000, v226
	v_rcp_f32_e32 v46, v46
	v_rcp_f32_e32 v47, v47
	v_pk_mul_f32 v[32:33], v[36:37], v[32:33]
	v_rsq_f32_e32 v144, v144
	v_pk_mul_f32 v[36:37], v[32:33], v[38:39]
	v_add_u32_e32 v38, 0x90, v126
	v_cvt_pk_bf16_f32 v35, v36, v37
	v_mad_i64_i32 v[36:37], s[22:23], v38, s65, v[114:115]
	v_lshl_add_u64 v[36:37], v[36:37], 0, s[68:69]
	v_pk_mul_f32 v[42:43], v[42:43], v[46:47]
	v_lshl_add_u64 v[36:37], v[36:37], 0, s[48:49]
	v_cvt_pk_bf16_f32 v32, v40, v41
	v_cvt_pk_bf16_f32 v33, v42, v43
	v_cvt_pk_bf16_f32 v34, v44, v45
	v_pk_mul_f32 v[28:29], v[28:29], v[144:145] op_sel_hi:[1,0]
	v_lshl_add_u64 v[36:37], v[36:37], 0, v[110:111]
	v_mul_f32_e32 v38, 0xbfb8aa3b, v28
	global_store_dwordx4 v[36:37], v[32:35], off
	v_exp_f32_e32 v38, v38
	v_pk_mul_f32 v[24:25], v[24:25], v[144:145] op_sel_hi:[1,0]
	v_mul_f32_e32 v33, 0xbfb8aa3b, v29
	v_exp_f32_e32 v33, v33
	v_add_f32_e32 v32, 1.0, v38
	v_pk_mul_f32 v[24:25], v[28:29], v[24:25]
	v_rcp_f32_e32 v32, v32
	v_add_f32_e32 v28, 1.0, v33
	v_rcp_f32_e32 v33, v28
	v_pk_mul_f32 v[28:29], v[30:31], v[144:145] op_sel_hi:[1,0]
	v_pk_mul_f32 v[20:21], v[20:21], v[144:145] op_sel_hi:[1,0]
	v_pk_mul_f32 v[26:27], v[26:27], v[144:145] op_sel_hi:[1,0]
	v_mul_f32_e32 v31, 0xbfb8aa3b, v29
	v_pk_mul_f32 v[24:25], v[24:25], v[32:33]
	v_mul_f32_e32 v32, 0xbfb8aa3b, v20
	v_pk_mul_f32 v[26:27], v[28:29], v[26:27]
	v_mul_f32_e32 v29, 0xbfb8aa3b, v21
	v_pk_mul_f32 v[16:17], v[16:17], v[144:145] op_sel_hi:[1,0]
	v_exp_f32_e32 v32, v32
	v_exp_f32_e32 v29, v29
	v_pk_mul_f32 v[16:17], v[20:21], v[16:17]
	v_pk_mul_f32 v[20:21], v[22:23], v[144:145] op_sel_hi:[1,0]
	v_mul_f32_e32 v30, 0xbfb8aa3b, v28
	v_mul_f32_e32 v22, 0xbfb8aa3b, v20
	v_mul_f32_e32 v23, 0xbfb8aa3b, v21
	v_exp_f32_e32 v22, v22
	v_exp_f32_e32 v23, v23
	v_add_f32_e32 v28, 1.0, v32
	v_add_f32_e32 v29, 1.0, v29
	v_exp_f32_e32 v30, v30
	v_exp_f32_e32 v31, v31
	v_rcp_f32_e32 v28, v28
	v_rcp_f32_e32 v29, v29
	v_add_f32_e32 v22, 1.0, v22
	v_add_f32_e32 v23, 1.0, v23
	v_rcp_f32_e32 v22, v22
	v_rcp_f32_e32 v23, v23
	v_add_f32_e32 v30, 1.0, v30
	v_add_f32_e32 v31, 1.0, v31
	v_pk_mul_f32 v[28:29], v[16:17], v[28:29]
	v_pk_mul_f32 v[16:17], v[18:19], v[144:145] op_sel_hi:[1,0]
	v_fmamk_f32 v142, v142, 0x3a800000, v226
	v_rcp_f32_e32 v30, v30
	v_rcp_f32_e32 v31, v31
	v_pk_mul_f32 v[16:17], v[20:21], v[16:17]
	v_rsq_f32_e32 v142, v142
	v_pk_mul_f32 v[20:21], v[16:17], v[22:23]
	v_add_u32_e32 v22, 0xa0, v126
	v_cvt_pk_bf16_f32 v19, v20, v21
	v_mad_i64_i32 v[20:21], s[22:23], v22, s65, v[114:115]
	v_lshl_add_u64 v[20:21], v[20:21], 0, s[68:69]
	v_pk_mul_f32 v[26:27], v[26:27], v[30:31]
	v_lshl_add_u64 v[20:21], v[20:21], 0, s[48:49]
	v_cvt_pk_bf16_f32 v16, v24, v25
	v_cvt_pk_bf16_f32 v17, v26, v27
	v_cvt_pk_bf16_f32 v18, v28, v29
	v_pk_mul_f32 v[12:13], v[12:13], v[142:143] op_sel_hi:[1,0]
	v_lshl_add_u64 v[20:21], v[20:21], 0, v[110:111]
	v_mul_f32_e32 v22, 0xbfb8aa3b, v12
	global_store_dwordx4 v[20:21], v[16:19], off
	v_exp_f32_e32 v22, v22
	v_pk_mul_f32 v[8:9], v[8:9], v[142:143] op_sel_hi:[1,0]
	v_mul_f32_e32 v17, 0xbfb8aa3b, v13
	v_exp_f32_e32 v17, v17
	v_add_f32_e32 v16, 1.0, v22
	v_pk_mul_f32 v[8:9], v[12:13], v[8:9]
	v_rcp_f32_e32 v16, v16
	v_add_f32_e32 v12, 1.0, v17
	v_rcp_f32_e32 v17, v12
	v_pk_mul_f32 v[12:13], v[14:15], v[142:143] op_sel_hi:[1,0]
	v_pk_mul_f32 v[4:5], v[4:5], v[142:143] op_sel_hi:[1,0]
	v_pk_mul_f32 v[10:11], v[10:11], v[142:143] op_sel_hi:[1,0]
	v_mul_f32_e32 v15, 0xbfb8aa3b, v13
	v_pk_mul_f32 v[8:9], v[8:9], v[16:17]
	v_mul_f32_e32 v16, 0xbfb8aa3b, v4
	v_pk_mul_f32 v[10:11], v[12:13], v[10:11]
	v_mul_f32_e32 v13, 0xbfb8aa3b, v5
	v_pk_mul_f32 v[0:1], v[0:1], v[142:143] op_sel_hi:[1,0]
	v_exp_f32_e32 v16, v16
	v_exp_f32_e32 v13, v13
	v_pk_mul_f32 v[0:1], v[4:5], v[0:1]
	v_pk_mul_f32 v[4:5], v[6:7], v[142:143] op_sel_hi:[1,0]
	v_mul_f32_e32 v14, 0xbfb8aa3b, v12
	v_mul_f32_e32 v6, 0xbfb8aa3b, v4
	v_mul_f32_e32 v7, 0xbfb8aa3b, v5
	v_exp_f32_e32 v6, v6
	v_exp_f32_e32 v7, v7
	v_add_f32_e32 v12, 1.0, v16
	v_add_f32_e32 v13, 1.0, v13
	v_exp_f32_e32 v14, v14
	v_exp_f32_e32 v15, v15
	v_rcp_f32_e32 v12, v12
	v_rcp_f32_e32 v13, v13
	v_add_f32_e32 v6, 1.0, v6
	v_add_f32_e32 v7, 1.0, v7
	v_rcp_f32_e32 v6, v6
	v_rcp_f32_e32 v7, v7
	v_add_f32_e32 v14, 1.0, v14
	v_add_f32_e32 v15, 1.0, v15
	v_pk_mul_f32 v[12:13], v[0:1], v[12:13]
	v_pk_mul_f32 v[0:1], v[2:3], v[142:143] op_sel_hi:[1,0]
	v_rcp_f32_e32 v14, v14
	v_rcp_f32_e32 v15, v15
	v_pk_mul_f32 v[0:1], v[4:5], v[0:1]
	v_cvt_pk_bf16_f32 v2, v12, v13
	v_pk_mul_f32 v[4:5], v[0:1], v[6:7]
	v_add_u32_e32 v6, 0xb0, v126
	v_cvt_pk_bf16_f32 v3, v4, v5
	v_mad_i64_i32 v[4:5], s[22:23], v6, s65, v[114:115]
	v_lshl_add_u64 v[4:5], v[4:5], 0, s[68:69]
	v_pk_mul_f32 v[10:11], v[10:11], v[14:15]
	v_lshl_add_u64 v[4:5], v[4:5], 0, s[48:49]
	v_cvt_pk_bf16_f32 v0, v8, v9
	v_cvt_pk_bf16_f32 v1, v10, v11
	v_lshl_add_u64 v[4:5], v[4:5], 0, v[110:111]
	s_mov_b64 s[6:7], -1
	global_store_dwordx4 v[4:5], v[0:3], off
	s_cbranch_vccnz .LBB0_1912
	s_andn2_b64 vcc, exec, s[30:31]
	s_cbranch_vccnz .LBB0_1911
	s_barrier
	s_branch .LBB0_1911
